# v045 + in-proj and gate-up K-loops: first half iteration peeled with C=0 on the first MFMA of each accumulator tile; per-unit zeroing of 128 accumulators removed
# speedup vs baseline: 1.0040x; 1.0019x over previous
; #define PG8_STAGE(bufoff, gbase, voff) do { _Pragma("unroll") for (int _i = 0; _i < 2; ++_i) \
;         __builtin_amdgcn_global_load_lds((const unsigned*)((const char*)(gbase) + (voff)[_i]), (PG8_LAS unsigned*)(lds + (bufoff) + ldsw + _i * 8192), 16, 0, 0); } while (0)
; #define PG8_LDA(dst, b, h) do { _Pragma("unroll") for (int m = 0; m < 4; ++m) _Pragma("unroll") for (int k = 0; k < 2; ++k) dst[m][k] = *(const PG8_LAS bf16x8*)(lds + PG8_SA(b, h) + aoff + m * 2048 + k * 1024); } while (0)
; #define PG8_LDB(dst, b, h) do { _Pragma("unroll") for (int n = 0; n < 2; ++n) _Pragma("unroll") for (int k = 0; k < 2; ++k) dst[n][k] = *(const PG8_LAS bf16x8*)(lds + PG8_SB(b, h) + boff + n * 2048 + k * 1024); } while (0)
; #define PG8_WAIT_V(n) asm volatile("s_waitcnt vmcnt(" #n ")" ::: "memory")
; #define PG8_WAIT_L(n) asm volatile("s_waitcnt lgkmcnt(" #n ")" ::: "memory")
; #define PG8_BAR __builtin_amdgcn_s_barrier()
; template <class Epi, class Sched, bool ALIGN_EPI = false, bool SP2 = false, bool PAIR_ACC = false>
; __device__ __forceinline__ void gemm_phase(PG8_LAS unsigned char* lds, const Gemm g, const Sched& S, const Epi& E) {
;     ...
;         const bool has_next = S.next(ui + 1, nxt);
;         const char* nA = has_next ? (const char*)g.A + (size_t)nxt.pm * tstep + (size_t)(nxt.pn / g.a_div) * g.a_sel : cA; const char* nB = has_next ? (const char*)g.Bt + (size_t)nxt.pn * tstep : cB;
;         for (int t = 0; t < nt; t += 2) {
;             const bool last = (t == nt - 2);
;             const char* a1 = cA + (size_t)(t + 1) * kstep;
;             const char* a2 = last ? nA : cA + (size_t)(t + 2) * kstep; const char* b2 = last ? nB : cB + (size_t)(t + 2) * kstep;
;             const char* a3 = a2 + kstep; const char* b3 = b2 + kstep;
;             if (last && has_next) S.a_ready(nxt);
;             if constexpr (SP2) {
;             PG8_LDB(B0, 0, 0); PG8_LDB(B1, 0, 1); PG8_SCHED; PG8_LDA(At, 0, 0); PG8_STAGE(PG8_SA(1, 1), a1 + hstep, voffA);
;             PG8_WAIT_V(8); PG8_WAIT_L(0); PG8_BAR; PG8_MMA(0, 0, At, B0); PG8_MMA(0, 1, At, B1); PG8_BAR; PG8_SCHED;
;     ...
;         for (int a = 0; a < 2; ++a)
; #pragma unroll
;             for (int b = 0; b < 2; ++b)
; #pragma unroll
;                 for (int m = 0; m < 4; ++m)
; #pragma unroll
;                     for (int n = 0; n < 2; ++n) acc[a][b][m][n] = (f32x4){0.f, 0.f, 0.f, 0.f};
.LBB0_189:
	s_mov_b32 s80, s21
	s_ashr_i32 s81, s21, 31
	s_lshl_b64 s[18:19], s[80:81], 19
	s_add_u32 s84, s23, s18
	s_addc_u32 s85, s61, s19
	s_mov_b32 s78, s17
	s_and_b64 s[18:19], s[82:83], exec
	s_cselect_b32 s13, s85, s11
	s_cselect_b32 s17, s84, s10
	s_ashr_i32 s79, s78, 31
	s_lshl_b64 s[18:19], s[78:79], 19
	s_add_u32 s86, s63, s18
	s_addc_u32 s87, s65, s19
	s_and_b64 s[18:19], s[82:83], exec
	s_cselect_b32 s20, s87, s15
	s_cselect_b32 s21, s86, s14
	s_add_u32 s10, s10, 0x40080
	s_addc_u32 s11, s11, 0
	s_add_u32 s30, s14, 0x100
	s_addc_u32 s38, s15, 0
	s_mov_b32 s39, -2
	s_waitcnt lgkmcnt(0)
	s_waitcnt vmcnt(0)
	ds_read_b128 v[130:133], v196
	ds_read_b128 v[134:137], v196 offset:1024
	ds_read_b128 v[138:141], v196 offset:2048
	ds_read_b128 v[142:145], v196 offset:3072
	ds_read_b128 v[178:181], v197
	ds_read_b128 v[182:185], v197 offset:1024
	ds_read_b128 v[186:189], v197 offset:2048
	ds_read_b128 v[190:193], v197 offset:3072
	s_add_u32 s14, s10, 0xfffc0080
	s_addc_u32 s15, s11, -1
	s_cmp_eq_u32 s39, 12
	s_cselect_b32 s19, s13, s15
	s_cselect_b32 s18, s17, s14
	s_cselect_b32 s15, s20, s38
	s_cselect_b32 s14, s21, s30
	v_lshl_add_u64 v[194:195], s[10:11], 0, v[170:171]
	s_add_i32 m0, s69, 0xc000
	ds_read_b128 v[206:209], v198
	ds_read_b128 v[210:213], v198 offset:1024
	ds_read_b128 v[214:217], v198 offset:2048
	ds_read_b128 v[218:221], v198 offset:3072
	ds_read_b128 v[222:225], v198 offset:4096
	ds_read_b128 v[226:229], v198 offset:5120
	ds_read_b128 v[230:233], v198 offset:6144
	ds_read_b128 v[234:237], v198 offset:7168
	global_load_lds_dwordx4 v[194:195], off
	v_lshl_add_u64 v[194:195], s[10:11], 0, v[174:175]
	s_add_i32 m0, s69, 0xe000
	s_nop 0
	global_load_lds_dwordx4 v[194:195], off
	s_waitcnt vmcnt(8)
	s_waitcnt lgkmcnt(0)
	s_barrier
	s_setprio 1
	s_waitcnt lgkmcnt(0)
	v_mfma_f32_16x16x32_bf16 v[126:129], v[130:133], v[206:209], 0
	v_mfma_f32_16x16x32_bf16 v[122:125], v[138:141], v[206:209], 0
	v_mfma_f32_16x16x32_bf16 v[110:113], v[130:133], v[214:217], 0
	v_mfma_f32_16x16x32_bf16 v[106:109], v[138:141], v[214:217], 0
	v_mfma_f32_16x16x32_bf16 v[94:97], v[130:133], v[222:225], 0
	v_mfma_f32_16x16x32_bf16 v[90:93], v[138:141], v[222:225], 0
	v_mfma_f32_16x16x32_bf16 v[78:81], v[130:133], v[230:233], 0
	v_mfma_f32_16x16x32_bf16 v[74:77], v[138:141], v[230:233], 0
	v_mfma_f32_16x16x32_bf16 v[126:129], v[134:137], v[210:213], v[126:129]
	v_mfma_f32_16x16x32_bf16 v[122:125], v[142:145], v[210:213], v[122:125]
	v_mfma_f32_16x16x32_bf16 v[110:113], v[134:137], v[218:221], v[110:113]
	v_mfma_f32_16x16x32_bf16 v[106:109], v[142:145], v[218:221], v[106:109]
	v_mfma_f32_16x16x32_bf16 v[94:97], v[134:137], v[226:229], v[94:97]
	v_mfma_f32_16x16x32_bf16 v[90:93], v[142:145], v[226:229], v[90:93]
	v_mfma_f32_16x16x32_bf16 v[78:81], v[134:137], v[234:237], v[78:81]
	v_mfma_f32_16x16x32_bf16 v[74:77], v[142:145], v[234:237], v[74:77]
	s_setprio 0
	s_setprio 1
	v_mfma_f32_16x16x32_bf16 v[118:121], v[178:181], v[206:209], 0
	v_mfma_f32_16x16x32_bf16 v[114:117], v[186:189], v[206:209], 0
	v_mfma_f32_16x16x32_bf16 v[102:105], v[178:181], v[214:217], 0
	v_mfma_f32_16x16x32_bf16 v[98:101], v[186:189], v[214:217], 0
	v_mfma_f32_16x16x32_bf16 v[86:89], v[178:181], v[222:225], 0
	v_mfma_f32_16x16x32_bf16 v[82:85], v[186:189], v[222:225], 0
	v_mfma_f32_16x16x32_bf16 v[70:73], v[178:181], v[230:233], 0
	v_mfma_f32_16x16x32_bf16 v[66:69], v[186:189], v[230:233], 0
	v_mfma_f32_16x16x32_bf16 v[118:121], v[182:185], v[210:213], v[118:121]
	v_mfma_f32_16x16x32_bf16 v[114:117], v[190:193], v[210:213], v[114:117]
	v_mfma_f32_16x16x32_bf16 v[102:105], v[182:185], v[218:221], v[102:105]
	v_mfma_f32_16x16x32_bf16 v[98:101], v[190:193], v[218:221], v[98:101]
	v_mfma_f32_16x16x32_bf16 v[86:89], v[182:185], v[226:229], v[86:89]
	v_mfma_f32_16x16x32_bf16 v[82:85], v[190:193], v[226:229], v[82:85]
	v_mfma_f32_16x16x32_bf16 v[70:73], v[182:185], v[234:237], v[70:73]
	v_mfma_f32_16x16x32_bf16 v[66:69], v[190:193], v[234:237], v[66:69]
	s_setprio 0
	s_barrier
; #define PG8_STAGE(bufoff, gbase, voff) do { _Pragma("unroll") for (int _i = 0; _i < 2; ++_i) \
;         __builtin_amdgcn_global_load_lds((const unsigned*)((const char*)(gbase) + (voff)[_i]), (PG8_LAS unsigned*)(lds + (bufoff) + ldsw + _i * 8192), 16, 0, 0); } while (0)
; #define PG8_LDA(dst, b, h) do { _Pragma("unroll") for (int m = 0; m < 4; ++m) _Pragma("unroll") for (int k = 0; k < 2; ++k) dst[m][k] = *(const PG8_LAS bf16x8*)(lds + PG8_SA(b, h) + aoff + m * 2048 + k * 1024); } while (0)
; #define PG8_MMA(ai, bj, At, Bt) do { __builtin_amdgcn_s_setprio(1); _Pragma("unroll") for (int m = 0; m < 4; ++m) _Pragma("unroll") for (int n = 0; n < 2; ++n) _Pragma("unroll") for (int k = 0; k < 2; ++k) \
;         acc[ai][bj][m][n] = __builtin_amdgcn_mfma_f32_16x16x32_bf16(Bt[n][k], At[m][k], acc[ai][bj][m][n], 0, 0, 0); __builtin_amdgcn_s_setprio(0); } while (0)
; #define PG8_WAIT_V(n) asm volatile("s_waitcnt vmcnt(" #n ")" ::: "memory")
; #define PG8_WAIT_L(n) asm volatile("s_waitcnt lgkmcnt(" #n ")" ::: "memory")
; #define PG8_BAR __builtin_amdgcn_s_barrier()
; #define PG8_SCHED __builtin_amdgcn_sched_barrier(0)
; template <class Epi, class Sched, bool ALIGN_EPI = false, bool SP2 = false, bool PAIR_ACC = false>
; __device__ __forceinline__ void gemm_phase(PG8_LAS unsigned char* lds, const Gemm g, const Sched& S, const Epi& E) {
;     ...
;             PG8_LDA(At, 0, 1); PG8_STAGE(PG8_SB(0, 0), b2, voffB); PG8_STAGE(PG8_SB(0, 1), b2 + hstep, voffB); PG8_STAGE(PG8_SA(0, 0), a2, voffA);
;             PG8_WAIT_V(8); PG8_WAIT_L(0); PG8_BAR; PG8_MMA(1, 0, At, B0); PG8_MMA(1, 1, At, B1); PG8_BAR; PG8_SCHED;
	s_add_i32 s40, s25, s67
	v_lshl_add_u64 v[194:195], s[14:15], 0, v[148:149]
	s_mov_b32 m0, s40
	ds_read_b128 v[206:209], v198 offset:16384
	ds_read_b128 v[210:213], v198 offset:17408
	ds_read_b128 v[214:217], v198 offset:18432
	ds_read_b128 v[218:221], v198 offset:19456
	ds_read_b128 v[222:225], v198 offset:20480
	ds_read_b128 v[226:229], v198 offset:21504
	ds_read_b128 v[230:233], v198 offset:22528
	ds_read_b128 v[234:237], v198 offset:23552
	global_load_lds_dwordx4 v[194:195], off
	s_add_i32 m0, s40, 0x2000
	s_add_u32 s40, s14, 0x40000
	v_lshl_add_u64 v[238:239], s[14:15], 0, v[152:153]
	s_addc_u32 s41, s15, 0
	s_add_i32 s79, s35, s67
	global_load_lds_dwordx4 v[238:239], off
	v_lshl_add_u64 v[240:241], s[40:41], 0, v[148:149]
	s_mov_b32 m0, s79
	v_lshl_add_u64 v[242:243], s[18:19], 0, v[150:151]
	global_load_lds_dwordx4 v[240:241], off
	v_lshl_add_u64 v[240:241], s[40:41], 0, v[152:153]
	s_add_i32 m0, s79, 0x2000
	s_nop 0
	global_load_lds_dwordx4 v[240:241], off
	v_lshl_add_u64 v[240:241], s[18:19], 0, v[146:147]
	s_mov_b32 m0, s69
	s_nop 0
	global_load_lds_dwordx4 v[240:241], off
	s_mov_b32 m0, s71
	s_nop 0
	global_load_lds_dwordx4 v[242:243], off
	s_waitcnt vmcnt(8)
	s_waitcnt lgkmcnt(0)
	s_barrier
	s_setprio 1
	s_waitcnt lgkmcnt(0)
	v_mfma_f32_16x16x32_bf16 v[62:65], v[130:133], v[206:209], 0
	v_mfma_f32_16x16x32_bf16 v[58:61], v[138:141], v[206:209], 0
	v_mfma_f32_16x16x32_bf16 v[46:49], v[130:133], v[214:217], 0
	v_mfma_f32_16x16x32_bf16 v[42:45], v[138:141], v[214:217], 0
	v_mfma_f32_16x16x32_bf16 v[30:33], v[130:133], v[222:225], 0
	v_mfma_f32_16x16x32_bf16 v[26:29], v[138:141], v[222:225], 0
	v_mfma_f32_16x16x32_bf16 v[14:17], v[130:133], v[230:233], 0
	v_mfma_f32_16x16x32_bf16 v[10:13], v[138:141], v[230:233], 0
	v_mfma_f32_16x16x32_bf16 v[62:65], v[134:137], v[210:213], v[62:65]
	v_mfma_f32_16x16x32_bf16 v[58:61], v[142:145], v[210:213], v[58:61]
	v_mfma_f32_16x16x32_bf16 v[46:49], v[134:137], v[218:221], v[46:49]
	v_mfma_f32_16x16x32_bf16 v[42:45], v[142:145], v[218:221], v[42:45]
	v_mfma_f32_16x16x32_bf16 v[30:33], v[134:137], v[226:229], v[30:33]
	v_mfma_f32_16x16x32_bf16 v[26:29], v[142:145], v[226:229], v[26:29]
	v_mfma_f32_16x16x32_bf16 v[14:17], v[134:137], v[234:237], v[14:17]
	v_mfma_f32_16x16x32_bf16 v[10:13], v[142:145], v[234:237], v[10:13]
	s_setprio 0
	s_setprio 1
	v_mfma_f32_16x16x32_bf16 v[54:57], v[178:181], v[206:209], 0
	v_mfma_f32_16x16x32_bf16 v[50:53], v[186:189], v[206:209], 0
	v_mfma_f32_16x16x32_bf16 v[38:41], v[178:181], v[214:217], 0
	v_mfma_f32_16x16x32_bf16 v[34:37], v[186:189], v[214:217], 0
	v_mfma_f32_16x16x32_bf16 v[22:25], v[178:181], v[222:225], 0
	v_mfma_f32_16x16x32_bf16 v[18:21], v[186:189], v[222:225], 0
	v_mfma_f32_16x16x32_bf16 v[6:9], v[178:181], v[230:233], 0
	v_mfma_f32_16x16x32_bf16 v[2:5], v[186:189], v[230:233], 0
	v_mfma_f32_16x16x32_bf16 v[54:57], v[182:185], v[210:213], v[54:57]
	v_mfma_f32_16x16x32_bf16 v[50:53], v[190:193], v[210:213], v[50:53]
	v_mfma_f32_16x16x32_bf16 v[38:41], v[182:185], v[218:221], v[38:41]
	v_mfma_f32_16x16x32_bf16 v[34:37], v[190:193], v[218:221], v[34:37]
	v_mfma_f32_16x16x32_bf16 v[22:25], v[182:185], v[226:229], v[22:25]
	v_mfma_f32_16x16x32_bf16 v[18:21], v[190:193], v[226:229], v[18:21]
	v_mfma_f32_16x16x32_bf16 v[6:9], v[182:185], v[234:237], v[6:9]
	v_mfma_f32_16x16x32_bf16 v[2:5], v[190:193], v[234:237], v[2:5]
	s_setprio 0
	s_barrier
	s_branch .Lpeel_mid_190

; #define PG8_STAGE(bufoff, gbase, voff) do { _Pragma("unroll") for (int _i = 0; _i < 2; ++_i) \
;         __builtin_amdgcn_global_load_lds((const unsigned*)((const char*)(gbase) + (voff)[_i]), (PG8_LAS unsigned*)(lds + (bufoff) + ldsw + _i * 8192), 16, 0, 0); } while (0)
; #define PG8_LDA(dst, b, h) do { _Pragma("unroll") for (int m = 0; m < 4; ++m) _Pragma("unroll") for (int k = 0; k < 2; ++k) dst[m][k] = *(const PG8_LAS bf16x8*)(lds + PG8_SA(b, h) + aoff + m * 2048 + k * 1024); } while (0)
; #define PG8_LDB(dst, b, h) do { _Pragma("unroll") for (int n = 0; n < 2; ++n) _Pragma("unroll") for (int k = 0; k < 2; ++k) dst[n][k] = *(const PG8_LAS bf16x8*)(lds + PG8_SB(b, h) + boff + n * 2048 + k * 1024); } while (0)
; #define PG8_MMA(ai, bj, At, Bt) do { __builtin_amdgcn_s_setprio(1); _Pragma("unroll") for (int m = 0; m < 4; ++m) _Pragma("unroll") for (int n = 0; n < 2; ++n) _Pragma("unroll") for (int k = 0; k < 2; ++k) \
;         acc[ai][bj][m][n] = __builtin_amdgcn_mfma_f32_16x16x32_bf16(Bt[n][k], At[m][k], acc[ai][bj][m][n], 0, 0, 0); __builtin_amdgcn_s_setprio(0); } while (0)
; #define PG8_WAIT_V(n) asm volatile("s_waitcnt vmcnt(" #n ")" ::: "memory")
; #define PG8_WAIT_L(n) asm volatile("s_waitcnt lgkmcnt(" #n ")" ::: "memory")
; #define PG8_BAR __builtin_amdgcn_s_barrier()
; #define PG8_SCHED __builtin_amdgcn_sched_barrier(0)
; template <class Epi, class Sched, bool ALIGN_EPI = false, bool SP2 = false, bool PAIR_ACC = false>
; __device__ __forceinline__ void gemm_phase(PG8_LAS unsigned char* lds, const Gemm g, const Sched& S, const Epi& E) {
;     ...
;             PG8_LDB(B0, 1, 0); PG8_LDB(B1, 1, 1); PG8_SCHED; PG8_LDA(At, 1, 0); PG8_STAGE(PG8_SA(0, 1), a2 + hstep, voffA);
;             PG8_WAIT_V(8); PG8_WAIT_L(0); PG8_BAR; PG8_MMA(0, 0, At, B0); PG8_MMA(0, 1, At, B1); PG8_BAR; PG8_SCHED;
.Lpeel_mid_190:
	s_add_i32 s40, 0, 0x18000
	s_add_i32 s41, 0, 0x1c000
	v_add_u32_e32 v142, s40, v173
	v_add_u32_e32 v154, s41, v173
	ds_read_b128 v[130:133], v142
	ds_read_b128 v[134:137], v142 offset:1024
	ds_read_b128 v[138:141], v142 offset:2048
	ds_read_b128 v[142:145], v142 offset:3072
	ds_read_b128 v[178:181], v154
	ds_read_b128 v[182:185], v154 offset:1024
	ds_read_b128 v[186:189], v154 offset:2048
	ds_read_b128 v[190:193], v154 offset:3072
	s_add_u32 s18, s18, 0x40000
	s_addc_u32 s19, s19, 0
	s_mov_b32 m0, s73
	v_lshl_add_u64 v[244:245], s[18:19], 0, v[146:147]
	ds_read_b128 v[206:209], v198 offset:32768
	ds_read_b128 v[210:213], v198 offset:33792
	ds_read_b128 v[214:217], v198 offset:34816
	ds_read_b128 v[218:221], v198 offset:35840
	ds_read_b128 v[222:225], v198 offset:36864
	ds_read_b128 v[226:229], v198 offset:37888
	ds_read_b128 v[230:233], v198 offset:38912
	ds_read_b128 v[234:237], v198 offset:39936
	global_load_lds_dwordx4 v[244:245], off
	v_lshl_add_u64 v[244:245], s[18:19], 0, v[150:151]
	s_mov_b32 m0, s36
	s_nop 0
	global_load_lds_dwordx4 v[244:245], off
	s_waitcnt vmcnt(8)
	s_waitcnt lgkmcnt(0)
	s_barrier
	s_setprio 1
	s_waitcnt lgkmcnt(0)
	v_mfma_f32_16x16x32_bf16 v[126:129], v[130:133], v[206:209], v[126:129]
	v_mfma_f32_16x16x32_bf16 v[122:125], v[138:141], v[206:209], v[122:125]
	v_mfma_f32_16x16x32_bf16 v[110:113], v[130:133], v[214:217], v[110:113]
	v_mfma_f32_16x16x32_bf16 v[106:109], v[138:141], v[214:217], v[106:109]
	v_mfma_f32_16x16x32_bf16 v[94:97], v[130:133], v[222:225], v[94:97]
	v_mfma_f32_16x16x32_bf16 v[90:93], v[138:141], v[222:225], v[90:93]
	v_mfma_f32_16x16x32_bf16 v[78:81], v[130:133], v[230:233], v[78:81]
	v_mfma_f32_16x16x32_bf16 v[74:77], v[138:141], v[230:233], v[74:77]
	v_mfma_f32_16x16x32_bf16 v[126:129], v[134:137], v[210:213], v[126:129]
	v_mfma_f32_16x16x32_bf16 v[122:125], v[142:145], v[210:213], v[122:125]
	v_mfma_f32_16x16x32_bf16 v[110:113], v[134:137], v[218:221], v[110:113]
	v_mfma_f32_16x16x32_bf16 v[106:109], v[142:145], v[218:221], v[106:109]
	v_mfma_f32_16x16x32_bf16 v[94:97], v[134:137], v[226:229], v[94:97]
	v_mfma_f32_16x16x32_bf16 v[90:93], v[142:145], v[226:229], v[90:93]
	v_mfma_f32_16x16x32_bf16 v[78:81], v[134:137], v[234:237], v[78:81]
	v_mfma_f32_16x16x32_bf16 v[74:77], v[142:145], v[234:237], v[74:77]
	s_setprio 0
	s_setprio 1
	v_mfma_f32_16x16x32_bf16 v[118:121], v[178:181], v[206:209], v[118:121]
	v_mfma_f32_16x16x32_bf16 v[114:117], v[186:189], v[206:209], v[114:117]
	v_mfma_f32_16x16x32_bf16 v[102:105], v[178:181], v[214:217], v[102:105]
	v_mfma_f32_16x16x32_bf16 v[98:101], v[186:189], v[214:217], v[98:101]
	v_mfma_f32_16x16x32_bf16 v[86:89], v[178:181], v[222:225], v[86:89]
	v_mfma_f32_16x16x32_bf16 v[82:85], v[186:189], v[222:225], v[82:85]
	v_mfma_f32_16x16x32_bf16 v[70:73], v[178:181], v[230:233], v[70:73]
	v_mfma_f32_16x16x32_bf16 v[66:69], v[186:189], v[230:233], v[66:69]
	v_mfma_f32_16x16x32_bf16 v[118:121], v[182:185], v[210:213], v[118:121]
	v_mfma_f32_16x16x32_bf16 v[114:117], v[190:193], v[210:213], v[114:117]
	v_mfma_f32_16x16x32_bf16 v[102:105], v[182:185], v[218:221], v[102:105]
	v_mfma_f32_16x16x32_bf16 v[98:101], v[190:193], v[218:221], v[98:101]
	v_mfma_f32_16x16x32_bf16 v[86:89], v[182:185], v[226:229], v[86:89]
	v_mfma_f32_16x16x32_bf16 v[82:85], v[190:193], v[226:229], v[82:85]
	v_mfma_f32_16x16x32_bf16 v[70:73], v[182:185], v[234:237], v[70:73]
	v_mfma_f32_16x16x32_bf16 v[66:69], v[190:193], v[234:237], v[66:69]
	s_setprio 0
	s_barrier
; #define PG8_STAGE(bufoff, gbase, voff) do { _Pragma("unroll") for (int _i = 0; _i < 2; ++_i) \
;         __builtin_amdgcn_global_load_lds((const unsigned*)((const char*)(gbase) + (voff)[_i]), (PG8_LAS unsigned*)(lds + (bufoff) + ldsw + _i * 8192), 16, 0, 0); } while (0)
; #define PG8_LDA(dst, b, h) do { _Pragma("unroll") for (int m = 0; m < 4; ++m) _Pragma("unroll") for (int k = 0; k < 2; ++k) dst[m][k] = *(const PG8_LAS bf16x8*)(lds + PG8_SA(b, h) + aoff + m * 2048 + k * 1024); } while (0)
; #define PG8_MMA(ai, bj, At, Bt) do { __builtin_amdgcn_s_setprio(1); _Pragma("unroll") for (int m = 0; m < 4; ++m) _Pragma("unroll") for (int n = 0; n < 2; ++n) _Pragma("unroll") for (int k = 0; k < 2; ++k) \
;         acc[ai][bj][m][n] = __builtin_amdgcn_mfma_f32_16x16x32_bf16(Bt[n][k], At[m][k], acc[ai][bj][m][n], 0, 0, 0); __builtin_amdgcn_s_setprio(0); } while (0)
; #define PG8_WAIT_V(n) asm volatile("s_waitcnt vmcnt(" #n ")" ::: "memory")
; #define PG8_WAIT_L(n) asm volatile("s_waitcnt lgkmcnt(" #n ")" ::: "memory")
; #define PG8_BAR __builtin_amdgcn_s_barrier()
; #define PG8_SCHED __builtin_amdgcn_sched_barrier(0)
; template <class Epi, class Sched, bool ALIGN_EPI = false, bool SP2 = false, bool PAIR_ACC = false>
; __device__ __forceinline__ void gemm_phase(PG8_LAS unsigned char* lds, const Gemm g, const Sched& S, const Epi& E) {
;     ...
;             PG8_LDA(At, 1, 1); PG8_STAGE(PG8_SB(1, 0), b3, voffB); PG8_STAGE(PG8_SB(1, 1), b3 + hstep, voffB); PG8_STAGE(PG8_SA(1, 0), a3, voffA);
;             PG8_WAIT_V(8); PG8_WAIT_L(0); PG8_BAR; PG8_MMA(1, 0, At, B0); PG8_MMA(1, 1, At, B1); PG8_BAR; PG8_SCHED;
;     ...
;         if constexpr (ALIGN_EPI) { if (wr == 0) PG8_BAR; }
	s_add_i32 s18, s40, s67
	v_lshl_add_u64 v[194:195], v[194:195], 0, s[50:51]
	s_mov_b32 m0, s18
	ds_read_b128 v[206:209], v198 offset:49152
	ds_read_b128 v[210:213], v198 offset:50176
	ds_read_b128 v[214:217], v198 offset:51200
	ds_read_b128 v[218:221], v198 offset:52224
	ds_read_b128 v[222:225], v198 offset:53248
	ds_read_b128 v[226:229], v198 offset:54272
	ds_read_b128 v[230:233], v198 offset:55296
	ds_read_b128 v[234:237], v198 offset:56320
	global_load_lds_dwordx4 v[194:195], off
	s_add_i32 m0, s18, 0x2000
	s_add_u32 s14, s14, 0x40080
	v_lshl_add_u64 v[194:195], v[238:239], 0, s[50:51]
	s_addc_u32 s15, s15, 0
	s_add_i32 s18, s41, s67
	global_load_lds_dwordx4 v[194:195], off
	v_lshl_add_u64 v[194:195], s[14:15], 0, v[148:149]
	s_mov_b32 m0, s18
	s_nop 0
	global_load_lds_dwordx4 v[194:195], off
	v_lshl_add_u64 v[194:195], s[14:15], 0, v[152:153]
	s_add_i32 m0, s18, 0x2000
	s_nop 0
	global_load_lds_dwordx4 v[194:195], off
	v_lshl_add_u64 v[194:195], v[240:241], 0, s[50:51]
	s_mov_b32 m0, s37
	s_nop 0
	global_load_lds_dwordx4 v[194:195], off
	v_lshl_add_u64 v[194:195], v[242:243], 0, s[50:51]
	s_mov_b32 m0, s75
	s_nop 0
	global_load_lds_dwordx4 v[194:195], off
	s_waitcnt vmcnt(8)
	s_waitcnt lgkmcnt(0)
	s_barrier
	s_setprio 1
	s_waitcnt lgkmcnt(0)
	v_mfma_f32_16x16x32_bf16 v[62:65], v[130:133], v[206:209], v[62:65]
	v_mfma_f32_16x16x32_bf16 v[58:61], v[138:141], v[206:209], v[58:61]
	v_mfma_f32_16x16x32_bf16 v[46:49], v[130:133], v[214:217], v[46:49]
	v_mfma_f32_16x16x32_bf16 v[42:45], v[138:141], v[214:217], v[42:45]
	v_mfma_f32_16x16x32_bf16 v[30:33], v[130:133], v[222:225], v[30:33]
	v_mfma_f32_16x16x32_bf16 v[26:29], v[138:141], v[222:225], v[26:29]
	v_mfma_f32_16x16x32_bf16 v[14:17], v[130:133], v[230:233], v[14:17]
	v_mfma_f32_16x16x32_bf16 v[10:13], v[138:141], v[230:233], v[10:13]
	v_mfma_f32_16x16x32_bf16 v[62:65], v[134:137], v[210:213], v[62:65]
	v_mfma_f32_16x16x32_bf16 v[58:61], v[142:145], v[210:213], v[58:61]
	v_mfma_f32_16x16x32_bf16 v[46:49], v[134:137], v[218:221], v[46:49]
	v_mfma_f32_16x16x32_bf16 v[42:45], v[142:145], v[218:221], v[42:45]
	v_mfma_f32_16x16x32_bf16 v[30:33], v[134:137], v[226:229], v[30:33]
	v_mfma_f32_16x16x32_bf16 v[26:29], v[142:145], v[226:229], v[26:29]
	v_mfma_f32_16x16x32_bf16 v[14:17], v[134:137], v[234:237], v[14:17]
	v_mfma_f32_16x16x32_bf16 v[10:13], v[142:145], v[234:237], v[10:13]
	s_setprio 0
	s_setprio 1
	v_mfma_f32_16x16x32_bf16 v[54:57], v[178:181], v[206:209], v[54:57]
	v_mfma_f32_16x16x32_bf16 v[50:53], v[186:189], v[206:209], v[50:53]
	v_mfma_f32_16x16x32_bf16 v[38:41], v[178:181], v[214:217], v[38:41]
	v_mfma_f32_16x16x32_bf16 v[34:37], v[186:189], v[214:217], v[34:37]
	v_mfma_f32_16x16x32_bf16 v[22:25], v[178:181], v[222:225], v[22:25]
	v_mfma_f32_16x16x32_bf16 v[18:21], v[186:189], v[222:225], v[18:21]
	v_mfma_f32_16x16x32_bf16 v[6:9], v[178:181], v[230:233], v[6:9]
	v_mfma_f32_16x16x32_bf16 v[2:5], v[186:189], v[230:233], v[2:5]
	v_mfma_f32_16x16x32_bf16 v[54:57], v[182:185], v[210:213], v[54:57]
	v_mfma_f32_16x16x32_bf16 v[50:53], v[190:193], v[210:213], v[50:53]
	v_mfma_f32_16x16x32_bf16 v[38:41], v[182:185], v[218:221], v[38:41]
	v_mfma_f32_16x16x32_bf16 v[34:37], v[190:193], v[218:221], v[34:37]
	v_mfma_f32_16x16x32_bf16 v[22:25], v[182:185], v[226:229], v[22:25]
	v_mfma_f32_16x16x32_bf16 v[18:21], v[190:193], v[226:229], v[18:21]
	v_mfma_f32_16x16x32_bf16 v[6:9], v[182:185], v[234:237], v[6:9]
	v_mfma_f32_16x16x32_bf16 v[2:5], v[190:193], v[234:237], v[2:5]
	s_setprio 0
	s_barrier
	s_add_i32 s39, s39, 2
	s_add_u32 s10, s10, 0x100
	s_addc_u32 s11, s11, 0
	s_add_u32 s30, s30, 0x100
	s_addc_u32 s38, s38, 0
	s_cmp_gt_u32 s39, 13
	s_cbranch_scc0 .LBB0_190
	s_and_b64 vcc, exec, s[52:53]
	s_cbranch_vccz .LBB0_193
	s_barrier

; #define PG8_STAGE(bufoff, gbase, voff) do { _Pragma("unroll") for (int _i = 0; _i < 2; ++_i) \
;         __builtin_amdgcn_global_load_lds((const unsigned*)((const char*)(gbase) + (voff)[_i]), (PG8_LAS unsigned*)(lds + (bufoff) + ldsw + _i * 8192), 16, 0, 0); } while (0)
; #define PG8_LDA(dst, b, h) do { _Pragma("unroll") for (int m = 0; m < 4; ++m) _Pragma("unroll") for (int k = 0; k < 2; ++k) dst[m][k] = *(const PG8_LAS bf16x8*)(lds + PG8_SA(b, h) + aoff + m * 2048 + k * 1024); } while (0)
; #define PG8_LDB(dst, b, h) do { _Pragma("unroll") for (int n = 0; n < 2; ++n) _Pragma("unroll") for (int k = 0; k < 2; ++k) dst[n][k] = *(const PG8_LAS bf16x8*)(lds + PG8_SB(b, h) + boff + n * 2048 + k * 1024); } while (0)
; #define PG8_WAIT_V(n) asm volatile("s_waitcnt vmcnt(" #n ")" ::: "memory")
; #define PG8_WAIT_L(n) asm volatile("s_waitcnt lgkmcnt(" #n ")" ::: "memory")
; #define PG8_BAR __builtin_amdgcn_s_barrier()
; template <class Epi, class Sched, bool ALIGN_EPI = false, bool SP2 = false, bool PAIR_ACC = false>
; __device__ __forceinline__ void gemm_phase(PG8_LAS unsigned char* lds, const Gemm g, const Sched& S, const Epi& E) {
;     ...
;         const bool has_next = S.next(ui + 1, nxt);
;         const char* nA = has_next ? (const char*)g.A + (size_t)nxt.pm * tstep + (size_t)(nxt.pn / g.a_div) * g.a_sel : cA; const char* nB = has_next ? (const char*)g.Bt + (size_t)nxt.pn * tstep : cB;
;         for (int t = 0; t < nt; t += 2) {
;             const bool last = (t == nt - 2);
;             const char* a1 = cA + (size_t)(t + 1) * kstep;
;             const char* a2 = last ? nA : cA + (size_t)(t + 2) * kstep; const char* b2 = last ? nB : cB + (size_t)(t + 2) * kstep;
;             const char* a3 = a2 + kstep; const char* b3 = b2 + kstep;
;             if (last && has_next) S.a_ready(nxt);
;             if constexpr (SP2) {
;             PG8_LDB(B0, 0, 0); PG8_LDB(B1, 0, 1); PG8_SCHED; PG8_LDA(At, 0, 0); PG8_STAGE(PG8_SA(1, 1), a1 + hstep, voffA);
;             PG8_WAIT_V(8); PG8_WAIT_L(0); PG8_BAR; PG8_MMA(0, 0, At, B0); PG8_MMA(0, 1, At, B1); PG8_BAR; PG8_SCHED;
;     ...
;         for (int a = 0; a < 2; ++a)
; #pragma unroll
;             for (int b = 0; b < 2; ++b)
; #pragma unroll
;                 for (int m = 0; m < 4; ++m)
; #pragma unroll
;                     for (int n = 0; n < 2; ++n) acc[a][b][m][n] = (f32x4){0.f, 0.f, 0.f, 0.f};
.LBB0_833:
	s_ashr_i32 s65, s64, 31
	s_lshl_b64 s[40:41], s[64:65], 19
	s_add_u32 s66, s4, s40
	s_addc_u32 s67, s5, s41
	s_and_b64 s[40:41], s[8:9], exec
	s_cselect_b32 s40, s67, s11
	s_cselect_b32 s41, s66, s10
	s_ashr_i32 s63, s62, 31
	s_lshl_b64 s[68:69], s[62:63], 19
	s_add_u32 s68, s23, s68
	s_addc_u32 s69, s24, s69
	s_and_b64 s[72:73], s[8:9], exec
	s_cselect_b32 s63, s69, s39
	s_cselect_b32 s65, s68, s38
	s_add_u32 s10, s10, 0x40080
	s_addc_u32 s11, s11, 0
	s_add_u32 s78, s38, 0x100
	s_addc_u32 s79, s39, 0
	s_mov_b32 s80, -2
	s_waitcnt vmcnt(0)
	ds_read_b128 v[74:77], v197
	ds_read_b128 v[78:81], v197 offset:1024
	ds_read_b128 v[82:85], v197 offset:2048
	ds_read_b128 v[86:89], v197 offset:3072
	ds_read_b128 v[90:93], v198
	ds_read_b128 v[94:97], v198 offset:1024
	ds_read_b128 v[98:101], v198 offset:2048
	ds_read_b128 v[106:109], v198 offset:3072
	s_add_u32 s38, s10, 0xfffc0080
	s_addc_u32 s39, s11, -1
	s_cmp_eq_u32 s80, 12
	s_cselect_b32 s73, s40, s39
	s_cselect_b32 s72, s41, s38
	s_cselect_b32 s39, s63, s79
	s_cselect_b32 s38, s65, s78
	v_lshl_add_u64 v[170:171], s[10:11], 0, v[186:187]
	s_add_i32 m0, s36, 0xc000
	ds_read_b128 v[162:165], v199
	ds_read_b128 v[166:169], v199 offset:1024
	ds_read_b128 v[210:213], v199 offset:2048
	ds_read_b128 v[214:217], v199 offset:3072
	ds_read_b128 v[218:221], v199 offset:4096
	ds_read_b128 v[222:225], v199 offset:5120
	ds_read_b128 v[226:229], v199 offset:6144
	ds_read_b128 v[230:233], v199 offset:7168
	global_load_lds_dwordx4 v[170:171], off
	v_lshl_add_u64 v[170:171], s[10:11], 0, v[188:189]
	s_add_i32 m0, s36, 0xe000
	s_nop 0
	global_load_lds_dwordx4 v[170:171], off
	s_waitcnt vmcnt(8)
	s_waitcnt lgkmcnt(0)
	s_barrier
	s_setprio 1
	s_waitcnt lgkmcnt(0)
	v_mfma_f32_16x16x32_bf16 v[150:153], v[74:77], v[162:165], 0
	v_mfma_f32_16x16x32_bf16 v[146:149], v[82:85], v[162:165], 0
	v_mfma_f32_16x16x32_bf16 v[134:137], v[74:77], v[210:213], 0
	v_mfma_f32_16x16x32_bf16 v[130:133], v[82:85], v[210:213], 0
	v_mfma_f32_16x16x32_bf16 v[118:121], v[74:77], v[218:221], 0
	v_mfma_f32_16x16x32_bf16 v[110:113], v[82:85], v[218:221], 0
	v_mfma_f32_16x16x32_bf16 v[114:117], v[74:77], v[226:229], 0
	v_mfma_f32_16x16x32_bf16 v[102:105], v[82:85], v[226:229], 0
	v_mfma_f32_16x16x32_bf16 v[150:153], v[78:81], v[166:169], v[150:153]
	v_mfma_f32_16x16x32_bf16 v[146:149], v[86:89], v[166:169], v[146:149]
	v_mfma_f32_16x16x32_bf16 v[134:137], v[78:81], v[214:217], v[134:137]
	v_mfma_f32_16x16x32_bf16 v[130:133], v[86:89], v[214:217], v[130:133]
	v_mfma_f32_16x16x32_bf16 v[118:121], v[78:81], v[222:225], v[118:121]
	v_mfma_f32_16x16x32_bf16 v[110:113], v[86:89], v[222:225], v[110:113]
	v_mfma_f32_16x16x32_bf16 v[114:117], v[78:81], v[230:233], v[114:117]
	v_mfma_f32_16x16x32_bf16 v[102:105], v[86:89], v[230:233], v[102:105]
	s_setprio 0
	s_setprio 1
	v_mfma_f32_16x16x32_bf16 v[158:161], v[90:93], v[162:165], 0
	v_mfma_f32_16x16x32_bf16 v[154:157], v[98:101], v[162:165], 0
	v_mfma_f32_16x16x32_bf16 v[142:145], v[90:93], v[210:213], 0
	v_mfma_f32_16x16x32_bf16 v[138:141], v[98:101], v[210:213], 0
	v_mfma_f32_16x16x32_bf16 v[126:129], v[90:93], v[218:221], 0
	v_mfma_f32_16x16x32_bf16 v[122:125], v[98:101], v[218:221], 0
	v_mfma_f32_16x16x32_bf16 v[70:73], v[90:93], v[226:229], 0
	v_mfma_f32_16x16x32_bf16 v[66:69], v[98:101], v[226:229], 0
	v_mfma_f32_16x16x32_bf16 v[158:161], v[94:97], v[166:169], v[158:161]
	v_mfma_f32_16x16x32_bf16 v[154:157], v[106:109], v[166:169], v[154:157]
	v_mfma_f32_16x16x32_bf16 v[142:145], v[94:97], v[214:217], v[142:145]
	v_mfma_f32_16x16x32_bf16 v[138:141], v[106:109], v[214:217], v[138:141]
	v_mfma_f32_16x16x32_bf16 v[126:129], v[94:97], v[222:225], v[126:129]
	v_mfma_f32_16x16x32_bf16 v[122:125], v[106:109], v[222:225], v[122:125]
	v_mfma_f32_16x16x32_bf16 v[70:73], v[94:97], v[230:233], v[70:73]
	v_mfma_f32_16x16x32_bf16 v[66:69], v[106:109], v[230:233], v[66:69]
	s_setprio 0
	s_barrier
; #define PG8_STAGE(bufoff, gbase, voff) do { _Pragma("unroll") for (int _i = 0; _i < 2; ++_i) \
;         __builtin_amdgcn_global_load_lds((const unsigned*)((const char*)(gbase) + (voff)[_i]), (PG8_LAS unsigned*)(lds + (bufoff) + ldsw + _i * 8192), 16, 0, 0); } while (0)
; #define PG8_LDA(dst, b, h) do { _Pragma("unroll") for (int m = 0; m < 4; ++m) _Pragma("unroll") for (int k = 0; k < 2; ++k) dst[m][k] = *(const PG8_LAS bf16x8*)(lds + PG8_SA(b, h) + aoff + m * 2048 + k * 1024); } while (0)
; #define PG8_MMA(ai, bj, At, Bt) do { __builtin_amdgcn_s_setprio(1); _Pragma("unroll") for (int m = 0; m < 4; ++m) _Pragma("unroll") for (int n = 0; n < 2; ++n) _Pragma("unroll") for (int k = 0; k < 2; ++k) \
;         acc[ai][bj][m][n] = __builtin_amdgcn_mfma_f32_16x16x32_bf16(Bt[n][k], At[m][k], acc[ai][bj][m][n], 0, 0, 0); __builtin_amdgcn_s_setprio(0); } while (0)
; #define PG8_WAIT_V(n) asm volatile("s_waitcnt vmcnt(" #n ")" ::: "memory")
; #define PG8_WAIT_L(n) asm volatile("s_waitcnt lgkmcnt(" #n ")" ::: "memory")
; #define PG8_BAR __builtin_amdgcn_s_barrier()
; #define PG8_SCHED __builtin_amdgcn_sched_barrier(0)
; template <class Epi, class Sched, bool ALIGN_EPI = false, bool SP2 = false, bool PAIR_ACC = false>
; __device__ __forceinline__ void gemm_phase(PG8_LAS unsigned char* lds, const Gemm g, const Sched& S, const Epi& E) {
;     ...
;             PG8_LDA(At, 0, 1); PG8_STAGE(PG8_SB(0, 0), b2, voffB); PG8_STAGE(PG8_SB(0, 1), b2 + hstep, voffB); PG8_STAGE(PG8_SA(0, 0), a2, voffA);
;             PG8_WAIT_V(8); PG8_WAIT_L(0); PG8_BAR; PG8_MMA(1, 0, At, B0); PG8_MMA(1, 1, At, B1); PG8_BAR; PG8_SCHED;
	s_add_i32 s81, s61, s25
	v_lshl_add_u64 v[170:171], s[38:39], 0, v[178:179]
	s_mov_b32 m0, s81
	ds_read_b128 v[162:165], v199 offset:16384
	ds_read_b128 v[166:169], v199 offset:17408
	ds_read_b128 v[210:213], v199 offset:18432
	ds_read_b128 v[214:217], v199 offset:19456
	ds_read_b128 v[218:221], v199 offset:20480
	ds_read_b128 v[222:225], v199 offset:21504
	ds_read_b128 v[226:229], v199 offset:22528
	ds_read_b128 v[230:233], v199 offset:23552
	global_load_lds_dwordx4 v[170:171], off
	s_add_i32 m0, s81, 0x2000
	s_add_u32 s82, s38, 0x40000
	v_lshl_add_u64 v[194:195], s[38:39], 0, v[174:175]
	s_addc_u32 s83, s39, 0
	s_add_i32 s81, s74, s25
	global_load_lds_dwordx4 v[194:195], off
	v_lshl_add_u64 v[234:235], s[82:83], 0, v[178:179]
	s_mov_b32 m0, s81
	v_lshl_add_u64 v[236:237], s[72:73], 0, v[176:177]
	global_load_lds_dwordx4 v[234:235], off
	v_lshl_add_u64 v[234:235], s[82:83], 0, v[174:175]
	s_add_i32 m0, s81, 0x2000
	s_nop 0
	global_load_lds_dwordx4 v[234:235], off
	v_lshl_add_u64 v[234:235], s[72:73], 0, v[180:181]
	s_mov_b32 m0, s36
	s_nop 0
	global_load_lds_dwordx4 v[234:235], off
	s_mov_b32 m0, s37
	s_nop 0
	global_load_lds_dwordx4 v[236:237], off
	s_waitcnt vmcnt(8)
	s_waitcnt lgkmcnt(0)
	s_barrier
	s_setprio 1
	s_waitcnt lgkmcnt(0)
	v_mfma_f32_16x16x32_bf16 v[54:57], v[74:77], v[162:165], 0
	v_mfma_f32_16x16x32_bf16 v[50:53], v[82:85], v[162:165], 0
	v_mfma_f32_16x16x32_bf16 v[38:41], v[74:77], v[210:213], 0
	v_mfma_f32_16x16x32_bf16 v[34:37], v[82:85], v[210:213], 0
	v_mfma_f32_16x16x32_bf16 v[22:25], v[74:77], v[218:221], 0
	v_mfma_f32_16x16x32_bf16 v[14:17], v[82:85], v[218:221], 0
	v_mfma_f32_16x16x32_bf16 v[18:21], v[74:77], v[226:229], 0
	v_mfma_f32_16x16x32_bf16 v[10:13], v[82:85], v[226:229], 0
	v_mfma_f32_16x16x32_bf16 v[54:57], v[78:81], v[166:169], v[54:57]
	v_mfma_f32_16x16x32_bf16 v[50:53], v[86:89], v[166:169], v[50:53]
	v_mfma_f32_16x16x32_bf16 v[38:41], v[78:81], v[214:217], v[38:41]
	v_mfma_f32_16x16x32_bf16 v[34:37], v[86:89], v[214:217], v[34:37]
	v_mfma_f32_16x16x32_bf16 v[22:25], v[78:81], v[222:225], v[22:25]
	v_mfma_f32_16x16x32_bf16 v[14:17], v[86:89], v[222:225], v[14:17]
	v_mfma_f32_16x16x32_bf16 v[18:21], v[78:81], v[230:233], v[18:21]
	v_mfma_f32_16x16x32_bf16 v[10:13], v[86:89], v[230:233], v[10:13]
	s_setprio 0
	s_setprio 1
	v_mfma_f32_16x16x32_bf16 v[62:65], v[90:93], v[162:165], 0
	v_mfma_f32_16x16x32_bf16 v[58:61], v[98:101], v[162:165], 0
	v_mfma_f32_16x16x32_bf16 v[46:49], v[90:93], v[210:213], 0
	v_mfma_f32_16x16x32_bf16 v[42:45], v[98:101], v[210:213], 0
	v_mfma_f32_16x16x32_bf16 v[30:33], v[90:93], v[218:221], 0
	v_mfma_f32_16x16x32_bf16 v[26:29], v[98:101], v[218:221], 0
	v_mfma_f32_16x16x32_bf16 v[6:9], v[90:93], v[226:229], 0
	v_mfma_f32_16x16x32_bf16 v[2:5], v[98:101], v[226:229], 0
	v_mfma_f32_16x16x32_bf16 v[62:65], v[94:97], v[166:169], v[62:65]
	v_mfma_f32_16x16x32_bf16 v[58:61], v[106:109], v[166:169], v[58:61]
	v_mfma_f32_16x16x32_bf16 v[46:49], v[94:97], v[214:217], v[46:49]
	v_mfma_f32_16x16x32_bf16 v[42:45], v[106:109], v[214:217], v[42:45]
	v_mfma_f32_16x16x32_bf16 v[30:33], v[94:97], v[222:225], v[30:33]
	v_mfma_f32_16x16x32_bf16 v[26:29], v[106:109], v[222:225], v[26:29]
	v_mfma_f32_16x16x32_bf16 v[6:9], v[94:97], v[230:233], v[6:9]
	v_mfma_f32_16x16x32_bf16 v[2:5], v[106:109], v[230:233], v[2:5]
	s_setprio 0
	s_barrier
	s_branch .Lpeel_mid_834

; #define PG8_STAGE(bufoff, gbase, voff) do { _Pragma("unroll") for (int _i = 0; _i < 2; ++_i) \
;         __builtin_amdgcn_global_load_lds((const unsigned*)((const char*)(gbase) + (voff)[_i]), (PG8_LAS unsigned*)(lds + (bufoff) + ldsw + _i * 8192), 16, 0, 0); } while (0)
; #define PG8_LDA(dst, b, h) do { _Pragma("unroll") for (int m = 0; m < 4; ++m) _Pragma("unroll") for (int k = 0; k < 2; ++k) dst[m][k] = *(const PG8_LAS bf16x8*)(lds + PG8_SA(b, h) + aoff + m * 2048 + k * 1024); } while (0)
; #define PG8_LDB(dst, b, h) do { _Pragma("unroll") for (int n = 0; n < 2; ++n) _Pragma("unroll") for (int k = 0; k < 2; ++k) dst[n][k] = *(const PG8_LAS bf16x8*)(lds + PG8_SB(b, h) + boff + n * 2048 + k * 1024); } while (0)
; #define PG8_MMA(ai, bj, At, Bt) do { __builtin_amdgcn_s_setprio(1); _Pragma("unroll") for (int m = 0; m < 4; ++m) _Pragma("unroll") for (int n = 0; n < 2; ++n) _Pragma("unroll") for (int k = 0; k < 2; ++k) \
;         acc[ai][bj][m][n] = __builtin_amdgcn_mfma_f32_16x16x32_bf16(Bt[n][k], At[m][k], acc[ai][bj][m][n], 0, 0, 0); __builtin_amdgcn_s_setprio(0); } while (0)
; #define PG8_WAIT_V(n) asm volatile("s_waitcnt vmcnt(" #n ")" ::: "memory")
; #define PG8_WAIT_L(n) asm volatile("s_waitcnt lgkmcnt(" #n ")" ::: "memory")
; #define PG8_BAR __builtin_amdgcn_s_barrier()
; #define PG8_SCHED __builtin_amdgcn_sched_barrier(0)
; template <class Epi, class Sched, bool ALIGN_EPI = false, bool SP2 = false, bool PAIR_ACC = false>
; __device__ __forceinline__ void gemm_phase(PG8_LAS unsigned char* lds, const Gemm g, const Sched& S, const Epi& E) {
;     ...
;             PG8_LDB(B0, 1, 0); PG8_LDB(B1, 1, 1); PG8_SCHED; PG8_LDA(At, 1, 0); PG8_STAGE(PG8_SA(0, 1), a2 + hstep, voffA);
;             PG8_WAIT_V(8); PG8_WAIT_L(0); PG8_BAR; PG8_MMA(0, 0, At, B0); PG8_MMA(0, 1, At, B1); PG8_BAR; PG8_SCHED;
.Lpeel_mid_834:
	s_add_i32 s81, 0, 0x18000
	s_add_i32 s82, 0, 0x1c000
	v_add_u32_e32 v86, s81, v183
	v_add_u32_e32 v106, s82, v183
	ds_read_b128 v[74:77], v86
	ds_read_b128 v[78:81], v86 offset:1024
	ds_read_b128 v[82:85], v86 offset:2048
	ds_read_b128 v[86:89], v86 offset:3072
	ds_read_b128 v[90:93], v106
	ds_read_b128 v[94:97], v106 offset:1024
	ds_read_b128 v[98:101], v106 offset:2048
	ds_read_b128 v[106:109], v106 offset:3072
	s_add_u32 s72, s72, 0x40000
	s_addc_u32 s73, s73, 0
	s_mov_b32 m0, s42
	v_lshl_add_u64 v[238:239], s[72:73], 0, v[180:181]
	ds_read_b128 v[162:165], v199 offset:32768
	ds_read_b128 v[166:169], v199 offset:33792
	ds_read_b128 v[210:213], v199 offset:34816
	ds_read_b128 v[214:217], v199 offset:35840
	ds_read_b128 v[218:221], v199 offset:36864
	ds_read_b128 v[222:225], v199 offset:37888
	ds_read_b128 v[226:229], v199 offset:38912
	ds_read_b128 v[230:233], v199 offset:39936
	global_load_lds_dwordx4 v[238:239], off
	v_lshl_add_u64 v[238:239], s[72:73], 0, v[176:177]
	s_mov_b32 m0, s43
	s_nop 0
	global_load_lds_dwordx4 v[238:239], off
	s_waitcnt vmcnt(8)
	s_waitcnt lgkmcnt(0)
	s_barrier
	s_setprio 1
	s_waitcnt lgkmcnt(0)
	v_mfma_f32_16x16x32_bf16 v[150:153], v[74:77], v[162:165], v[150:153]
	v_mfma_f32_16x16x32_bf16 v[146:149], v[82:85], v[162:165], v[146:149]
	v_mfma_f32_16x16x32_bf16 v[134:137], v[74:77], v[210:213], v[134:137]
	v_mfma_f32_16x16x32_bf16 v[130:133], v[82:85], v[210:213], v[130:133]
	v_mfma_f32_16x16x32_bf16 v[118:121], v[74:77], v[218:221], v[118:121]
	v_mfma_f32_16x16x32_bf16 v[110:113], v[82:85], v[218:221], v[110:113]
	v_mfma_f32_16x16x32_bf16 v[114:117], v[74:77], v[226:229], v[114:117]
	v_mfma_f32_16x16x32_bf16 v[102:105], v[82:85], v[226:229], v[102:105]
	v_mfma_f32_16x16x32_bf16 v[150:153], v[78:81], v[166:169], v[150:153]
	v_mfma_f32_16x16x32_bf16 v[146:149], v[86:89], v[166:169], v[146:149]
	v_mfma_f32_16x16x32_bf16 v[134:137], v[78:81], v[214:217], v[134:137]
	v_mfma_f32_16x16x32_bf16 v[130:133], v[86:89], v[214:217], v[130:133]
	v_mfma_f32_16x16x32_bf16 v[118:121], v[78:81], v[222:225], v[118:121]
	v_mfma_f32_16x16x32_bf16 v[110:113], v[86:89], v[222:225], v[110:113]
	v_mfma_f32_16x16x32_bf16 v[114:117], v[78:81], v[230:233], v[114:117]
	v_mfma_f32_16x16x32_bf16 v[102:105], v[86:89], v[230:233], v[102:105]
	s_setprio 0
	s_setprio 1
	v_mfma_f32_16x16x32_bf16 v[158:161], v[90:93], v[162:165], v[158:161]
	v_mfma_f32_16x16x32_bf16 v[154:157], v[98:101], v[162:165], v[154:157]
	v_mfma_f32_16x16x32_bf16 v[142:145], v[90:93], v[210:213], v[142:145]
	v_mfma_f32_16x16x32_bf16 v[138:141], v[98:101], v[210:213], v[138:141]
	v_mfma_f32_16x16x32_bf16 v[126:129], v[90:93], v[218:221], v[126:129]
	v_mfma_f32_16x16x32_bf16 v[122:125], v[98:101], v[218:221], v[122:125]
	v_mfma_f32_16x16x32_bf16 v[70:73], v[90:93], v[226:229], v[70:73]
	v_mfma_f32_16x16x32_bf16 v[66:69], v[98:101], v[226:229], v[66:69]
	v_mfma_f32_16x16x32_bf16 v[158:161], v[94:97], v[166:169], v[158:161]
	v_mfma_f32_16x16x32_bf16 v[154:157], v[106:109], v[166:169], v[154:157]
	v_mfma_f32_16x16x32_bf16 v[142:145], v[94:97], v[214:217], v[142:145]
	v_mfma_f32_16x16x32_bf16 v[138:141], v[106:109], v[214:217], v[138:141]
	v_mfma_f32_16x16x32_bf16 v[126:129], v[94:97], v[222:225], v[126:129]
	v_mfma_f32_16x16x32_bf16 v[122:125], v[106:109], v[222:225], v[122:125]
	v_mfma_f32_16x16x32_bf16 v[70:73], v[94:97], v[230:233], v[70:73]
	v_mfma_f32_16x16x32_bf16 v[66:69], v[106:109], v[230:233], v[66:69]
	s_setprio 0
	s_barrier
; #define PG8_STAGE(bufoff, gbase, voff) do { _Pragma("unroll") for (int _i = 0; _i < 2; ++_i) \
;         __builtin_amdgcn_global_load_lds((const unsigned*)((const char*)(gbase) + (voff)[_i]), (PG8_LAS unsigned*)(lds + (bufoff) + ldsw + _i * 8192), 16, 0, 0); } while (0)
; #define PG8_LDA(dst, b, h) do { _Pragma("unroll") for (int m = 0; m < 4; ++m) _Pragma("unroll") for (int k = 0; k < 2; ++k) dst[m][k] = *(const PG8_LAS bf16x8*)(lds + PG8_SA(b, h) + aoff + m * 2048 + k * 1024); } while (0)
; #define PG8_MMA(ai, bj, At, Bt) do { __builtin_amdgcn_s_setprio(1); _Pragma("unroll") for (int m = 0; m < 4; ++m) _Pragma("unroll") for (int n = 0; n < 2; ++n) _Pragma("unroll") for (int k = 0; k < 2; ++k) \
;         acc[ai][bj][m][n] = __builtin_amdgcn_mfma_f32_16x16x32_bf16(Bt[n][k], At[m][k], acc[ai][bj][m][n], 0, 0, 0); __builtin_amdgcn_s_setprio(0); } while (0)
; #define PG8_WAIT_V(n) asm volatile("s_waitcnt vmcnt(" #n ")" ::: "memory")
; #define PG8_WAIT_L(n) asm volatile("s_waitcnt lgkmcnt(" #n ")" ::: "memory")
; #define PG8_BAR __builtin_amdgcn_s_barrier()
; #define PG8_SCHED __builtin_amdgcn_sched_barrier(0)
; template <class Epi, class Sched, bool ALIGN_EPI = false, bool SP2 = false, bool PAIR_ACC = false>
; __device__ __forceinline__ void gemm_phase(PG8_LAS unsigned char* lds, const Gemm g, const Sched& S, const Epi& E) {
;     ...
;             PG8_LDA(At, 1, 1); PG8_STAGE(PG8_SB(1, 0), b3, voffB); PG8_STAGE(PG8_SB(1, 1), b3 + hstep, voffB); PG8_STAGE(PG8_SA(1, 0), a3, voffA);
;             PG8_WAIT_V(8); PG8_WAIT_L(0); PG8_BAR; PG8_MMA(1, 0, At, B0); PG8_MMA(1, 1, At, B1); PG8_BAR; PG8_SCHED;
;     ...
;         if constexpr (ALIGN_EPI) { if (wr == 0) PG8_BAR; }
	s_add_i32 s72, s81, s25
	v_lshl_add_u64 v[170:171], v[170:171], 0, s[48:49]
	s_mov_b32 m0, s72
	ds_read_b128 v[162:165], v199 offset:49152
	ds_read_b128 v[166:169], v199 offset:50176
	ds_read_b128 v[210:213], v199 offset:51200
	ds_read_b128 v[214:217], v199 offset:52224
	ds_read_b128 v[218:221], v199 offset:53248
	ds_read_b128 v[222:225], v199 offset:54272
	ds_read_b128 v[226:229], v199 offset:55296
	ds_read_b128 v[230:233], v199 offset:56320
	global_load_lds_dwordx4 v[170:171], off
	s_add_i32 m0, s72, 0x2000
	s_add_u32 s38, s38, 0x40080
	v_lshl_add_u64 v[170:171], v[194:195], 0, s[48:49]
	s_addc_u32 s39, s39, 0
	s_add_i32 s72, s82, s25
	global_load_lds_dwordx4 v[170:171], off
	v_lshl_add_u64 v[170:171], s[38:39], 0, v[178:179]
	s_mov_b32 m0, s72
	s_nop 0
	global_load_lds_dwordx4 v[170:171], off
	v_lshl_add_u64 v[170:171], s[38:39], 0, v[174:175]
	s_add_i32 m0, s72, 0x2000
	s_nop 0
	global_load_lds_dwordx4 v[170:171], off
	v_lshl_add_u64 v[170:171], v[234:235], 0, s[48:49]
	s_mov_b32 m0, s45
	s_nop 0
	global_load_lds_dwordx4 v[170:171], off
	v_lshl_add_u64 v[170:171], v[236:237], 0, s[48:49]
	s_mov_b32 m0, s46
	s_nop 0
	global_load_lds_dwordx4 v[170:171], off
	s_waitcnt vmcnt(8)
	s_waitcnt lgkmcnt(0)
	s_barrier
	s_setprio 1
	s_waitcnt lgkmcnt(0)
	v_mfma_f32_16x16x32_bf16 v[54:57], v[74:77], v[162:165], v[54:57]
	v_mfma_f32_16x16x32_bf16 v[50:53], v[82:85], v[162:165], v[50:53]
	v_mfma_f32_16x16x32_bf16 v[38:41], v[74:77], v[210:213], v[38:41]
	v_mfma_f32_16x16x32_bf16 v[34:37], v[82:85], v[210:213], v[34:37]
	v_mfma_f32_16x16x32_bf16 v[22:25], v[74:77], v[218:221], v[22:25]
	v_mfma_f32_16x16x32_bf16 v[14:17], v[82:85], v[218:221], v[14:17]
	v_mfma_f32_16x16x32_bf16 v[18:21], v[74:77], v[226:229], v[18:21]
	v_mfma_f32_16x16x32_bf16 v[10:13], v[82:85], v[226:229], v[10:13]
	v_mfma_f32_16x16x32_bf16 v[54:57], v[78:81], v[166:169], v[54:57]
	v_mfma_f32_16x16x32_bf16 v[50:53], v[86:89], v[166:169], v[50:53]
	v_mfma_f32_16x16x32_bf16 v[38:41], v[78:81], v[214:217], v[38:41]
	v_mfma_f32_16x16x32_bf16 v[34:37], v[86:89], v[214:217], v[34:37]
	v_mfma_f32_16x16x32_bf16 v[22:25], v[78:81], v[222:225], v[22:25]
	v_mfma_f32_16x16x32_bf16 v[14:17], v[86:89], v[222:225], v[14:17]
	v_mfma_f32_16x16x32_bf16 v[18:21], v[78:81], v[230:233], v[18:21]
	v_mfma_f32_16x16x32_bf16 v[10:13], v[86:89], v[230:233], v[10:13]
	s_setprio 0
	s_setprio 1
	v_mfma_f32_16x16x32_bf16 v[62:65], v[90:93], v[162:165], v[62:65]
	v_mfma_f32_16x16x32_bf16 v[58:61], v[98:101], v[162:165], v[58:61]
	v_mfma_f32_16x16x32_bf16 v[46:49], v[90:93], v[210:213], v[46:49]
	v_mfma_f32_16x16x32_bf16 v[42:45], v[98:101], v[210:213], v[42:45]
	v_mfma_f32_16x16x32_bf16 v[30:33], v[90:93], v[218:221], v[30:33]
	v_mfma_f32_16x16x32_bf16 v[26:29], v[98:101], v[218:221], v[26:29]
	v_mfma_f32_16x16x32_bf16 v[6:9], v[90:93], v[226:229], v[6:9]
	v_mfma_f32_16x16x32_bf16 v[2:5], v[98:101], v[226:229], v[2:5]
	v_mfma_f32_16x16x32_bf16 v[62:65], v[94:97], v[166:169], v[62:65]
	v_mfma_f32_16x16x32_bf16 v[58:61], v[106:109], v[166:169], v[58:61]
	v_mfma_f32_16x16x32_bf16 v[46:49], v[94:97], v[214:217], v[46:49]
	v_mfma_f32_16x16x32_bf16 v[42:45], v[106:109], v[214:217], v[42:45]
	v_mfma_f32_16x16x32_bf16 v[30:33], v[94:97], v[222:225], v[30:33]
	v_mfma_f32_16x16x32_bf16 v[26:29], v[106:109], v[222:225], v[26:29]
	v_mfma_f32_16x16x32_bf16 v[6:9], v[94:97], v[230:233], v[6:9]
	v_mfma_f32_16x16x32_bf16 v[2:5], v[106:109], v[230:233], v[2:5]
	s_setprio 0
	s_barrier
	s_add_i32 s80, s80, 2
	s_add_u32 s10, s10, 0x100
	s_addc_u32 s11, s11, 0
	s_add_u32 s78, s78, 0x100
	s_addc_u32 s79, s79, 0
	s_cmp_gt_u32 s80, 13
	s_cbranch_scc0 .LBB0_834
	s_and_b64 vcc, exec, s[50:51]
	s_cbranch_vccz .LBB0_837
	s_barrier

; #define PG8_STAGE(bufoff, gbase, voff) do { _Pragma("unroll") for (int _i = 0; _i < 2; ++_i) \
;         __builtin_amdgcn_global_load_lds((const unsigned*)((const char*)(gbase) + (voff)[_i]), (PG8_LAS unsigned*)(lds + (bufoff) + ldsw + _i * 8192), 16, 0, 0); } while (0)
; #define PG8_LDA(dst, b, h) do { _Pragma("unroll") for (int m = 0; m < 4; ++m) _Pragma("unroll") for (int k = 0; k < 2; ++k) dst[m][k] = *(const PG8_LAS bf16x8*)(lds + PG8_SA(b, h) + aoff + m * 2048 + k * 1024); } while (0)
; #define PG8_LDB(dst, b, h) do { _Pragma("unroll") for (int n = 0; n < 2; ++n) _Pragma("unroll") for (int k = 0; k < 2; ++k) dst[n][k] = *(const PG8_LAS bf16x8*)(lds + PG8_SB(b, h) + boff + n * 2048 + k * 1024); } while (0)
; #define PG8_MMA(ai, bj, At, Bt) do { __builtin_amdgcn_s_setprio(1); _Pragma("unroll") for (int m = 0; m < 4; ++m) _Pragma("unroll") for (int n = 0; n < 2; ++n) _Pragma("unroll") for (int k = 0; k < 2; ++k) \
;         acc[ai][bj][m][n] = __builtin_amdgcn_mfma_f32_16x16x32_bf16(Bt[n][k], At[m][k], acc[ai][bj][m][n], 0, 0, 0); __builtin_amdgcn_s_setprio(0); } while (0)
; #define PG8_WAIT_V(n) asm volatile("s_waitcnt vmcnt(" #n ")" ::: "memory")
; #define PG8_WAIT_L(n) asm volatile("s_waitcnt lgkmcnt(" #n ")" ::: "memory")
; template <class Epi, class Sched, bool ALIGN_EPI = false, bool SP2 = false, bool PAIR_ACC = false>
; __device__ __forceinline__ void gemm_phase(PG8_LAS unsigned char* lds, const Gemm g, const Sched& S, const Epi& E) {
;     ...
;         const char* nA = has_next ? (const char*)g.A + (size_t)nxt.pm * tstep + (size_t)(nxt.pn / g.a_div) * g.a_sel : cA; const char* nB = has_next ? (const char*)g.Bt + (size_t)nxt.pn * tstep : cB;
;         for (int t = 0; t < nt; t += 2) {
;             const bool last = (t == nt - 2);
;             const char* a1 = cA + (size_t)(t + 1) * kstep;
;             const char* a2 = last ? nA : cA + (size_t)(t + 2) * kstep; const char* b2 = last ? nB : cB + (size_t)(t + 2) * kstep;
;             const char* a3 = a2 + kstep; const char* b3 = b2 + kstep;
;             if (last && has_next) S.a_ready(nxt);
;             if constexpr (SP2) {
;             PG8_LDB(B0, 0, 0); PG8_LDB(B1, 0, 1); PG8_SCHED; PG8_LDA(At, 0, 0); PG8_STAGE(PG8_SA(1, 1), a1 + hstep, voffA);
;             PG8_WAIT_V(8); PG8_WAIT_L(0); PG8_BAR; PG8_MMA(0, 0, At, B0); PG8_MMA(0, 1, At, B1); PG8_BAR; PG8_SCHED;
.LBB0_1092:
	s_mov_b32 s78, s23
	s_ashr_i32 s79, s23, 31
	s_lshl_b64 s[20:21], s[78:79], 19
	s_add_u32 s82, s59, s20
	s_addc_u32 s83, s61, s21
	s_mov_b32 s76, s19
	s_and_b64 s[20:21], s[80:81], exec
	s_cselect_b32 s15, s83, s13
	s_cselect_b32 s19, s82, s12
	s_ashr_i32 s77, s76, 31
	s_lshl_b64 s[20:21], s[76:77], 19
	s_add_u32 s84, s63, s20
	s_addc_u32 s85, s69, s21
	s_and_b64 s[20:21], s[80:81], exec
	s_cselect_b32 s22, s85, s17
	s_cselect_b32 s23, s84, s16
	s_add_u32 s12, s12, 0x40080
	s_addc_u32 s13, s13, 0
	s_add_u32 s30, s16, 0x100
	s_addc_u32 s42, s17, 0
	s_mov_b32 s43, -2
	s_waitcnt lgkmcnt(0)
	s_waitcnt vmcnt(0)
	ds_read_b128 v[130:133], v195
	ds_read_b128 v[134:137], v195 offset:1024
	ds_read_b128 v[138:141], v195 offset:2048
	ds_read_b128 v[142:145], v195 offset:3072
	ds_read_b128 v[176:179], v196
	ds_read_b128 v[180:183], v196 offset:1024
	ds_read_b128 v[184:187], v196 offset:2048
	ds_read_b128 v[188:191], v196 offset:3072
	s_add_u32 s16, s12, 0xfffc0080
	s_addc_u32 s17, s13, -1
	s_cmp_eq_u32 s43, 12
	s_cselect_b32 s21, s15, s17
	s_cselect_b32 s20, s19, s16
	s_cselect_b32 s17, s22, s42
	s_cselect_b32 s16, s23, s30
	v_lshl_add_u64 v[192:193], s[12:13], 0, v[170:171]
	s_add_i32 m0, s73, 0xc000
	ds_read_b128 v[200:203], v197
	ds_read_b128 v[204:207], v197 offset:1024
	ds_read_b128 v[208:211], v197 offset:2048
	ds_read_b128 v[212:215], v197 offset:3072
	ds_read_b128 v[216:219], v197 offset:4096
	ds_read_b128 v[220:223], v197 offset:5120
	ds_read_b128 v[224:227], v197 offset:6144
	ds_read_b128 v[228:231], v197 offset:7168
	global_load_lds_dwordx4 v[192:193], off
	v_lshl_add_u64 v[192:193], s[12:13], 0, v[172:173]
	s_add_i32 m0, s73, 0xe000
	s_nop 0
	global_load_lds_dwordx4 v[192:193], off
	s_waitcnt vmcnt(8)
	s_waitcnt lgkmcnt(0)
	s_barrier
	s_setprio 1
	s_waitcnt lgkmcnt(0)
	v_mfma_f32_16x16x32_bf16 v[126:129], v[130:133], v[200:203], 0
	v_mfma_f32_16x16x32_bf16 v[122:125], v[138:141], v[200:203], 0
	v_mfma_f32_16x16x32_bf16 v[110:113], v[130:133], v[208:211], 0
	v_mfma_f32_16x16x32_bf16 v[106:109], v[138:141], v[208:211], 0
	v_mfma_f32_16x16x32_bf16 v[94:97], v[130:133], v[216:219], 0
	v_mfma_f32_16x16x32_bf16 v[90:93], v[138:141], v[216:219], 0
	v_mfma_f32_16x16x32_bf16 v[78:81], v[130:133], v[224:227], 0
	v_mfma_f32_16x16x32_bf16 v[74:77], v[138:141], v[224:227], 0
	v_mfma_f32_16x16x32_bf16 v[126:129], v[134:137], v[204:207], v[126:129]
	v_mfma_f32_16x16x32_bf16 v[122:125], v[142:145], v[204:207], v[122:125]
	v_mfma_f32_16x16x32_bf16 v[110:113], v[134:137], v[212:215], v[110:113]
	v_mfma_f32_16x16x32_bf16 v[106:109], v[142:145], v[212:215], v[106:109]
	v_mfma_f32_16x16x32_bf16 v[94:97], v[134:137], v[220:223], v[94:97]
	v_mfma_f32_16x16x32_bf16 v[90:93], v[142:145], v[220:223], v[90:93]
	v_mfma_f32_16x16x32_bf16 v[78:81], v[134:137], v[228:231], v[78:81]
	v_mfma_f32_16x16x32_bf16 v[74:77], v[142:145], v[228:231], v[74:77]
	s_setprio 0
	s_setprio 1
	v_mfma_f32_16x16x32_bf16 v[118:121], v[176:179], v[200:203], 0
	v_mfma_f32_16x16x32_bf16 v[114:117], v[184:187], v[200:203], 0
	v_mfma_f32_16x16x32_bf16 v[102:105], v[176:179], v[208:211], 0
	v_mfma_f32_16x16x32_bf16 v[98:101], v[184:187], v[208:211], 0
	v_mfma_f32_16x16x32_bf16 v[86:89], v[176:179], v[216:219], 0
	v_mfma_f32_16x16x32_bf16 v[82:85], v[184:187], v[216:219], 0
	v_mfma_f32_16x16x32_bf16 v[70:73], v[176:179], v[224:227], 0
	v_mfma_f32_16x16x32_bf16 v[66:69], v[184:187], v[224:227], 0
	v_mfma_f32_16x16x32_bf16 v[118:121], v[180:183], v[204:207], v[118:121]
	v_mfma_f32_16x16x32_bf16 v[114:117], v[188:191], v[204:207], v[114:117]
	v_mfma_f32_16x16x32_bf16 v[102:105], v[180:183], v[212:215], v[102:105]
	v_mfma_f32_16x16x32_bf16 v[98:101], v[188:191], v[212:215], v[98:101]
	v_mfma_f32_16x16x32_bf16 v[86:89], v[180:183], v[220:223], v[86:89]
	v_mfma_f32_16x16x32_bf16 v[82:85], v[188:191], v[220:223], v[82:85]
	v_mfma_f32_16x16x32_bf16 v[70:73], v[180:183], v[228:231], v[70:73]
	v_mfma_f32_16x16x32_bf16 v[66:69], v[188:191], v[228:231], v[66:69]
	s_setprio 0
	s_barrier
; #define PG8_STAGE(bufoff, gbase, voff) do { _Pragma("unroll") for (int _i = 0; _i < 2; ++_i) \
;         __builtin_amdgcn_global_load_lds((const unsigned*)((const char*)(gbase) + (voff)[_i]), (PG8_LAS unsigned*)(lds + (bufoff) + ldsw + _i * 8192), 16, 0, 0); } while (0)
; #define PG8_LDA(dst, b, h) do { _Pragma("unroll") for (int m = 0; m < 4; ++m) _Pragma("unroll") for (int k = 0; k < 2; ++k) dst[m][k] = *(const PG8_LAS bf16x8*)(lds + PG8_SA(b, h) + aoff + m * 2048 + k * 1024); } while (0)
; #define PG8_MMA(ai, bj, At, Bt) do { __builtin_amdgcn_s_setprio(1); _Pragma("unroll") for (int m = 0; m < 4; ++m) _Pragma("unroll") for (int n = 0; n < 2; ++n) _Pragma("unroll") for (int k = 0; k < 2; ++k) \
;         acc[ai][bj][m][n] = __builtin_amdgcn_mfma_f32_16x16x32_bf16(Bt[n][k], At[m][k], acc[ai][bj][m][n], 0, 0, 0); __builtin_amdgcn_s_setprio(0); } while (0)
; #define PG8_WAIT_V(n) asm volatile("s_waitcnt vmcnt(" #n ")" ::: "memory")
; #define PG8_WAIT_L(n) asm volatile("s_waitcnt lgkmcnt(" #n ")" ::: "memory")
; #define PG8_BAR __builtin_amdgcn_s_barrier()
; #define PG8_SCHED __builtin_amdgcn_sched_barrier(0)
; template <class Epi, class Sched, bool ALIGN_EPI = false, bool SP2 = false, bool PAIR_ACC = false>
; __device__ __forceinline__ void gemm_phase(PG8_LAS unsigned char* lds, const Gemm g, const Sched& S, const Epi& E) {
;     ...
;             PG8_LDA(At, 0, 1); PG8_STAGE(PG8_SB(0, 0), b2, voffB); PG8_STAGE(PG8_SB(0, 1), b2 + hstep, voffB); PG8_STAGE(PG8_SA(0, 0), a2, voffA);
;             PG8_WAIT_V(8); PG8_WAIT_L(0); PG8_BAR; PG8_MMA(1, 0, At, B0); PG8_MMA(1, 1, At, B1); PG8_BAR; PG8_SCHED;
	s_add_i32 s77, s34, s71
	v_lshl_add_u64 v[192:193], s[16:17], 0, v[148:149]
	s_mov_b32 m0, s77
	ds_read_b128 v[200:203], v197 offset:16384
	ds_read_b128 v[204:207], v197 offset:17408
	ds_read_b128 v[208:211], v197 offset:18432
	ds_read_b128 v[212:215], v197 offset:19456
	ds_read_b128 v[216:219], v197 offset:20480
	ds_read_b128 v[220:223], v197 offset:21504
	ds_read_b128 v[224:227], v197 offset:22528
	ds_read_b128 v[228:231], v197 offset:23552
	global_load_lds_dwordx4 v[192:193], off
	s_add_i32 m0, s77, 0x2000
	s_add_u32 s86, s16, 0x40000
	v_lshl_add_u64 v[232:233], s[16:17], 0, v[152:153]
	s_addc_u32 s87, s17, 0
	s_add_i32 s77, s35, s71
	global_load_lds_dwordx4 v[232:233], off
	v_lshl_add_u64 v[234:235], s[86:87], 0, v[148:149]
	s_mov_b32 m0, s77
	v_lshl_add_u64 v[236:237], s[20:21], 0, v[150:151]
	global_load_lds_dwordx4 v[234:235], off
	v_lshl_add_u64 v[234:235], s[86:87], 0, v[152:153]
	s_add_i32 m0, s77, 0x2000
	s_nop 0
	global_load_lds_dwordx4 v[234:235], off
	v_lshl_add_u64 v[234:235], s[20:21], 0, v[146:147]
	s_mov_b32 m0, s73
	s_nop 0
	global_load_lds_dwordx4 v[234:235], off
	s_mov_b32 m0, s75
	s_nop 0
	global_load_lds_dwordx4 v[236:237], off
	s_waitcnt vmcnt(8)
	s_waitcnt lgkmcnt(0)
	s_barrier
	s_setprio 1
	s_waitcnt lgkmcnt(0)
	v_mfma_f32_16x16x32_bf16 v[62:65], v[130:133], v[200:203], 0
	v_mfma_f32_16x16x32_bf16 v[58:61], v[138:141], v[200:203], 0
	v_mfma_f32_16x16x32_bf16 v[46:49], v[130:133], v[208:211], 0
	v_mfma_f32_16x16x32_bf16 v[42:45], v[138:141], v[208:211], 0
	v_mfma_f32_16x16x32_bf16 v[30:33], v[130:133], v[216:219], 0
	v_mfma_f32_16x16x32_bf16 v[26:29], v[138:141], v[216:219], 0
	v_mfma_f32_16x16x32_bf16 v[14:17], v[130:133], v[224:227], 0
	v_mfma_f32_16x16x32_bf16 v[10:13], v[138:141], v[224:227], 0
	v_mfma_f32_16x16x32_bf16 v[62:65], v[134:137], v[204:207], v[62:65]
	v_mfma_f32_16x16x32_bf16 v[58:61], v[142:145], v[204:207], v[58:61]
	v_mfma_f32_16x16x32_bf16 v[46:49], v[134:137], v[212:215], v[46:49]
	v_mfma_f32_16x16x32_bf16 v[42:45], v[142:145], v[212:215], v[42:45]
	v_mfma_f32_16x16x32_bf16 v[30:33], v[134:137], v[220:223], v[30:33]
	v_mfma_f32_16x16x32_bf16 v[26:29], v[142:145], v[220:223], v[26:29]
	v_mfma_f32_16x16x32_bf16 v[14:17], v[134:137], v[228:231], v[14:17]
	v_mfma_f32_16x16x32_bf16 v[10:13], v[142:145], v[228:231], v[10:13]
	s_setprio 0
	s_setprio 1
	v_mfma_f32_16x16x32_bf16 v[54:57], v[176:179], v[200:203], 0
	v_mfma_f32_16x16x32_bf16 v[50:53], v[184:187], v[200:203], 0
	v_mfma_f32_16x16x32_bf16 v[38:41], v[176:179], v[208:211], 0
	v_mfma_f32_16x16x32_bf16 v[34:37], v[184:187], v[208:211], 0
	v_mfma_f32_16x16x32_bf16 v[22:25], v[176:179], v[216:219], 0
	v_mfma_f32_16x16x32_bf16 v[18:21], v[184:187], v[216:219], 0
	v_mfma_f32_16x16x32_bf16 v[6:9], v[176:179], v[224:227], 0
	v_mfma_f32_16x16x32_bf16 v[2:5], v[184:187], v[224:227], 0
	v_mfma_f32_16x16x32_bf16 v[54:57], v[180:183], v[204:207], v[54:57]
	v_mfma_f32_16x16x32_bf16 v[50:53], v[188:191], v[204:207], v[50:53]
	v_mfma_f32_16x16x32_bf16 v[38:41], v[180:183], v[212:215], v[38:41]
	v_mfma_f32_16x16x32_bf16 v[34:37], v[188:191], v[212:215], v[34:37]
	v_mfma_f32_16x16x32_bf16 v[22:25], v[180:183], v[220:223], v[22:25]
	v_mfma_f32_16x16x32_bf16 v[18:21], v[188:191], v[220:223], v[18:21]
	v_mfma_f32_16x16x32_bf16 v[6:9], v[180:183], v[228:231], v[6:9]
	v_mfma_f32_16x16x32_bf16 v[2:5], v[188:191], v[228:231], v[2:5]
	s_setprio 0
	s_barrier
	s_branch .Lpeel_mid_1093

; #define PG8_STAGE(bufoff, gbase, voff) do { _Pragma("unroll") for (int _i = 0; _i < 2; ++_i) \
;         __builtin_amdgcn_global_load_lds((const unsigned*)((const char*)(gbase) + (voff)[_i]), (PG8_LAS unsigned*)(lds + (bufoff) + ldsw + _i * 8192), 16, 0, 0); } while (0)
; #define PG8_LDA(dst, b, h) do { _Pragma("unroll") for (int m = 0; m < 4; ++m) _Pragma("unroll") for (int k = 0; k < 2; ++k) dst[m][k] = *(const PG8_LAS bf16x8*)(lds + PG8_SA(b, h) + aoff + m * 2048 + k * 1024); } while (0)
; #define PG8_LDB(dst, b, h) do { _Pragma("unroll") for (int n = 0; n < 2; ++n) _Pragma("unroll") for (int k = 0; k < 2; ++k) dst[n][k] = *(const PG8_LAS bf16x8*)(lds + PG8_SB(b, h) + boff + n * 2048 + k * 1024); } while (0)
; #define PG8_MMA(ai, bj, At, Bt) do { __builtin_amdgcn_s_setprio(1); _Pragma("unroll") for (int m = 0; m < 4; ++m) _Pragma("unroll") for (int n = 0; n < 2; ++n) _Pragma("unroll") for (int k = 0; k < 2; ++k) \
;         acc[ai][bj][m][n] = __builtin_amdgcn_mfma_f32_16x16x32_bf16(Bt[n][k], At[m][k], acc[ai][bj][m][n], 0, 0, 0); __builtin_amdgcn_s_setprio(0); } while (0)
; #define PG8_WAIT_V(n) asm volatile("s_waitcnt vmcnt(" #n ")" ::: "memory")
; #define PG8_WAIT_L(n) asm volatile("s_waitcnt lgkmcnt(" #n ")" ::: "memory")
; #define PG8_BAR __builtin_amdgcn_s_barrier()
; #define PG8_SCHED __builtin_amdgcn_sched_barrier(0)
; template <class Epi, class Sched, bool ALIGN_EPI = false, bool SP2 = false, bool PAIR_ACC = false>
; __device__ __forceinline__ void gemm_phase(PG8_LAS unsigned char* lds, const Gemm g, const Sched& S, const Epi& E) {
;     ...
;             PG8_LDB(B0, 1, 0); PG8_LDB(B1, 1, 1); PG8_SCHED; PG8_LDA(At, 1, 0); PG8_STAGE(PG8_SA(0, 1), a2 + hstep, voffA);
;             PG8_WAIT_V(8); PG8_WAIT_L(0); PG8_BAR; PG8_MMA(0, 0, At, B0); PG8_MMA(0, 1, At, B1); PG8_BAR; PG8_SCHED;
.Lpeel_mid_1093:
	s_add_i32 s77, 0, 0x18000
	s_add_i32 s79, 0, 0x1c000
	v_add_u32_e32 v142, s77, v194
	v_add_u32_e32 v154, s79, v194
	ds_read_b128 v[130:133], v142
	ds_read_b128 v[134:137], v142 offset:1024
	ds_read_b128 v[138:141], v142 offset:2048
	ds_read_b128 v[142:145], v142 offset:3072
	ds_read_b128 v[176:179], v154
	ds_read_b128 v[180:183], v154 offset:1024
	ds_read_b128 v[184:187], v154 offset:2048
	ds_read_b128 v[188:191], v154 offset:3072
	s_add_u32 s20, s20, 0x40000
	s_addc_u32 s21, s21, 0
	s_mov_b32 m0, s44
	v_lshl_add_u64 v[238:239], s[20:21], 0, v[146:147]
	ds_read_b128 v[200:203], v197 offset:32768
	ds_read_b128 v[204:207], v197 offset:33792
	ds_read_b128 v[208:211], v197 offset:34816
	ds_read_b128 v[212:215], v197 offset:35840
	ds_read_b128 v[216:219], v197 offset:36864
	ds_read_b128 v[220:223], v197 offset:37888
	ds_read_b128 v[224:227], v197 offset:38912
	ds_read_b128 v[228:231], v197 offset:39936
	global_load_lds_dwordx4 v[238:239], off
	v_lshl_add_u64 v[238:239], s[20:21], 0, v[150:151]
	s_mov_b32 m0, s45
	s_nop 0
	global_load_lds_dwordx4 v[238:239], off
	s_waitcnt vmcnt(8)
	s_waitcnt lgkmcnt(0)
	s_barrier
	s_setprio 1
	s_waitcnt lgkmcnt(0)
	v_mfma_f32_16x16x32_bf16 v[126:129], v[130:133], v[200:203], v[126:129]
	v_mfma_f32_16x16x32_bf16 v[122:125], v[138:141], v[200:203], v[122:125]
	v_mfma_f32_16x16x32_bf16 v[110:113], v[130:133], v[208:211], v[110:113]
	v_mfma_f32_16x16x32_bf16 v[106:109], v[138:141], v[208:211], v[106:109]
	v_mfma_f32_16x16x32_bf16 v[94:97], v[130:133], v[216:219], v[94:97]
	v_mfma_f32_16x16x32_bf16 v[90:93], v[138:141], v[216:219], v[90:93]
	v_mfma_f32_16x16x32_bf16 v[78:81], v[130:133], v[224:227], v[78:81]
	v_mfma_f32_16x16x32_bf16 v[74:77], v[138:141], v[224:227], v[74:77]
	v_mfma_f32_16x16x32_bf16 v[126:129], v[134:137], v[204:207], v[126:129]
	v_mfma_f32_16x16x32_bf16 v[122:125], v[142:145], v[204:207], v[122:125]
	v_mfma_f32_16x16x32_bf16 v[110:113], v[134:137], v[212:215], v[110:113]
	v_mfma_f32_16x16x32_bf16 v[106:109], v[142:145], v[212:215], v[106:109]
	v_mfma_f32_16x16x32_bf16 v[94:97], v[134:137], v[220:223], v[94:97]
	v_mfma_f32_16x16x32_bf16 v[90:93], v[142:145], v[220:223], v[90:93]
	v_mfma_f32_16x16x32_bf16 v[78:81], v[134:137], v[228:231], v[78:81]
	v_mfma_f32_16x16x32_bf16 v[74:77], v[142:145], v[228:231], v[74:77]
	s_setprio 0
	s_setprio 1
	v_mfma_f32_16x16x32_bf16 v[118:121], v[176:179], v[200:203], v[118:121]
	v_mfma_f32_16x16x32_bf16 v[114:117], v[184:187], v[200:203], v[114:117]
	v_mfma_f32_16x16x32_bf16 v[102:105], v[176:179], v[208:211], v[102:105]
	v_mfma_f32_16x16x32_bf16 v[98:101], v[184:187], v[208:211], v[98:101]
	v_mfma_f32_16x16x32_bf16 v[86:89], v[176:179], v[216:219], v[86:89]
	v_mfma_f32_16x16x32_bf16 v[82:85], v[184:187], v[216:219], v[82:85]
	v_mfma_f32_16x16x32_bf16 v[70:73], v[176:179], v[224:227], v[70:73]
	v_mfma_f32_16x16x32_bf16 v[66:69], v[184:187], v[224:227], v[66:69]
	v_mfma_f32_16x16x32_bf16 v[118:121], v[180:183], v[204:207], v[118:121]
	v_mfma_f32_16x16x32_bf16 v[114:117], v[188:191], v[204:207], v[114:117]
	v_mfma_f32_16x16x32_bf16 v[102:105], v[180:183], v[212:215], v[102:105]
	v_mfma_f32_16x16x32_bf16 v[98:101], v[188:191], v[212:215], v[98:101]
	v_mfma_f32_16x16x32_bf16 v[86:89], v[180:183], v[220:223], v[86:89]
	v_mfma_f32_16x16x32_bf16 v[82:85], v[188:191], v[220:223], v[82:85]
	v_mfma_f32_16x16x32_bf16 v[70:73], v[180:183], v[228:231], v[70:73]
	v_mfma_f32_16x16x32_bf16 v[66:69], v[188:191], v[228:231], v[66:69]
	s_setprio 0
	s_barrier
; #define PG8_STAGE(bufoff, gbase, voff) do { _Pragma("unroll") for (int _i = 0; _i < 2; ++_i) \
;         __builtin_amdgcn_global_load_lds((const unsigned*)((const char*)(gbase) + (voff)[_i]), (PG8_LAS unsigned*)(lds + (bufoff) + ldsw + _i * 8192), 16, 0, 0); } while (0)
; #define PG8_LDA(dst, b, h) do { _Pragma("unroll") for (int m = 0; m < 4; ++m) _Pragma("unroll") for (int k = 0; k < 2; ++k) dst[m][k] = *(const PG8_LAS bf16x8*)(lds + PG8_SA(b, h) + aoff + m * 2048 + k * 1024); } while (0)
; #define PG8_MMA(ai, bj, At, Bt) do { __builtin_amdgcn_s_setprio(1); _Pragma("unroll") for (int m = 0; m < 4; ++m) _Pragma("unroll") for (int n = 0; n < 2; ++n) _Pragma("unroll") for (int k = 0; k < 2; ++k) \
;         acc[ai][bj][m][n] = __builtin_amdgcn_mfma_f32_16x16x32_bf16(Bt[n][k], At[m][k], acc[ai][bj][m][n], 0, 0, 0); __builtin_amdgcn_s_setprio(0); } while (0)
; #define PG8_WAIT_V(n) asm volatile("s_waitcnt vmcnt(" #n ")" ::: "memory")
; #define PG8_WAIT_L(n) asm volatile("s_waitcnt lgkmcnt(" #n ")" ::: "memory")
; #define PG8_BAR __builtin_amdgcn_s_barrier()
; #define PG8_SCHED __builtin_amdgcn_sched_barrier(0)
; template <class Epi, class Sched, bool ALIGN_EPI = false, bool SP2 = false, bool PAIR_ACC = false>
; __device__ __forceinline__ void gemm_phase(PG8_LAS unsigned char* lds, const Gemm g, const Sched& S, const Epi& E) {
;     ...
;             PG8_LDA(At, 1, 1); PG8_STAGE(PG8_SB(1, 0), b3, voffB); PG8_STAGE(PG8_SB(1, 1), b3 + hstep, voffB); PG8_STAGE(PG8_SA(1, 0), a3, voffA);
;             PG8_WAIT_V(8); PG8_WAIT_L(0); PG8_BAR; PG8_MMA(1, 0, At, B0); PG8_MMA(1, 1, At, B1); PG8_BAR; PG8_SCHED;
;     ...
;         if constexpr (ALIGN_EPI) { if (wr == 0) PG8_BAR; }
	s_add_i32 s20, s77, s71
	v_lshl_add_u64 v[192:193], v[192:193], 0, s[48:49]
	s_mov_b32 m0, s20
	ds_read_b128 v[200:203], v197 offset:49152
	ds_read_b128 v[204:207], v197 offset:50176
	ds_read_b128 v[208:211], v197 offset:51200
	ds_read_b128 v[212:215], v197 offset:52224
	ds_read_b128 v[216:219], v197 offset:53248
	ds_read_b128 v[220:223], v197 offset:54272
	ds_read_b128 v[224:227], v197 offset:55296
	ds_read_b128 v[228:231], v197 offset:56320
	global_load_lds_dwordx4 v[192:193], off
	s_add_i32 m0, s20, 0x2000
	s_add_u32 s16, s16, 0x40080
	v_lshl_add_u64 v[192:193], v[232:233], 0, s[48:49]
	s_addc_u32 s17, s17, 0
	s_add_i32 s20, s79, s71
	global_load_lds_dwordx4 v[192:193], off
	v_lshl_add_u64 v[192:193], s[16:17], 0, v[148:149]
	s_mov_b32 m0, s20
	s_nop 0
	global_load_lds_dwordx4 v[192:193], off
	v_lshl_add_u64 v[192:193], s[16:17], 0, v[152:153]
	s_add_i32 m0, s20, 0x2000
	s_nop 0
	global_load_lds_dwordx4 v[192:193], off
	v_lshl_add_u64 v[192:193], v[234:235], 0, s[48:49]
	s_mov_b32 m0, s36
	s_nop 0
	global_load_lds_dwordx4 v[192:193], off
	v_lshl_add_u64 v[192:193], v[236:237], 0, s[48:49]
	s_mov_b32 m0, s37
	s_nop 0
	global_load_lds_dwordx4 v[192:193], off
	s_waitcnt vmcnt(8)
	s_waitcnt lgkmcnt(0)
	s_barrier
	s_setprio 1
	s_waitcnt lgkmcnt(0)
	v_mfma_f32_16x16x32_bf16 v[62:65], v[130:133], v[200:203], v[62:65]
	v_mfma_f32_16x16x32_bf16 v[58:61], v[138:141], v[200:203], v[58:61]
	v_mfma_f32_16x16x32_bf16 v[46:49], v[130:133], v[208:211], v[46:49]
	v_mfma_f32_16x16x32_bf16 v[42:45], v[138:141], v[208:211], v[42:45]
	v_mfma_f32_16x16x32_bf16 v[30:33], v[130:133], v[216:219], v[30:33]
	v_mfma_f32_16x16x32_bf16 v[26:29], v[138:141], v[216:219], v[26:29]
	v_mfma_f32_16x16x32_bf16 v[14:17], v[130:133], v[224:227], v[14:17]
	v_mfma_f32_16x16x32_bf16 v[10:13], v[138:141], v[224:227], v[10:13]
	v_mfma_f32_16x16x32_bf16 v[62:65], v[134:137], v[204:207], v[62:65]
	v_mfma_f32_16x16x32_bf16 v[58:61], v[142:145], v[204:207], v[58:61]
	v_mfma_f32_16x16x32_bf16 v[46:49], v[134:137], v[212:215], v[46:49]
	v_mfma_f32_16x16x32_bf16 v[42:45], v[142:145], v[212:215], v[42:45]
	v_mfma_f32_16x16x32_bf16 v[30:33], v[134:137], v[220:223], v[30:33]
	v_mfma_f32_16x16x32_bf16 v[26:29], v[142:145], v[220:223], v[26:29]
	v_mfma_f32_16x16x32_bf16 v[14:17], v[134:137], v[228:231], v[14:17]
	v_mfma_f32_16x16x32_bf16 v[10:13], v[142:145], v[228:231], v[10:13]
	s_setprio 0
	s_setprio 1
	v_mfma_f32_16x16x32_bf16 v[54:57], v[176:179], v[200:203], v[54:57]
	v_mfma_f32_16x16x32_bf16 v[50:53], v[184:187], v[200:203], v[50:53]
	v_mfma_f32_16x16x32_bf16 v[38:41], v[176:179], v[208:211], v[38:41]
	v_mfma_f32_16x16x32_bf16 v[34:37], v[184:187], v[208:211], v[34:37]
	v_mfma_f32_16x16x32_bf16 v[22:25], v[176:179], v[216:219], v[22:25]
	v_mfma_f32_16x16x32_bf16 v[18:21], v[184:187], v[216:219], v[18:21]
	v_mfma_f32_16x16x32_bf16 v[6:9], v[176:179], v[224:227], v[6:9]
	v_mfma_f32_16x16x32_bf16 v[2:5], v[184:187], v[224:227], v[2:5]
	v_mfma_f32_16x16x32_bf16 v[54:57], v[180:183], v[204:207], v[54:57]
	v_mfma_f32_16x16x32_bf16 v[50:53], v[188:191], v[204:207], v[50:53]
	v_mfma_f32_16x16x32_bf16 v[38:41], v[180:183], v[212:215], v[38:41]
	v_mfma_f32_16x16x32_bf16 v[34:37], v[188:191], v[212:215], v[34:37]
	v_mfma_f32_16x16x32_bf16 v[22:25], v[180:183], v[220:223], v[22:25]
	v_mfma_f32_16x16x32_bf16 v[18:21], v[188:191], v[220:223], v[18:21]
	v_mfma_f32_16x16x32_bf16 v[6:9], v[180:183], v[228:231], v[6:9]
	v_mfma_f32_16x16x32_bf16 v[2:5], v[188:191], v[228:231], v[2:5]
	s_setprio 0
	s_barrier
	s_add_i32 s43, s43, 2
	s_add_u32 s12, s12, 0x100
	s_addc_u32 s13, s13, 0
	s_add_u32 s30, s30, 0x100
	s_addc_u32 s42, s42, 0
	s_cmp_gt_u32 s43, 13
	s_cbranch_scc0 .LBB0_1093
	s_and_b64 vcc, exec, s[50:51]
	s_cbranch_vccz .LBB0_1096
	s_barrier

; #define PG8_STAGE(bufoff, gbase, voff) do { _Pragma("unroll") for (int _i = 0; _i < 2; ++_i) \
;         __builtin_amdgcn_global_load_lds((const unsigned*)((const char*)(gbase) + (voff)[_i]), (PG8_LAS unsigned*)(lds + (bufoff) + ldsw + _i * 8192), 16, 0, 0); } while (0)
; #define PG8_LDA(dst, b, h) do { _Pragma("unroll") for (int m = 0; m < 4; ++m) _Pragma("unroll") for (int k = 0; k < 2; ++k) dst[m][k] = *(const PG8_LAS bf16x8*)(lds + PG8_SA(b, h) + aoff + m * 2048 + k * 1024); } while (0)
; #define PG8_LDB(dst, b, h) do { _Pragma("unroll") for (int n = 0; n < 2; ++n) _Pragma("unroll") for (int k = 0; k < 2; ++k) dst[n][k] = *(const PG8_LAS bf16x8*)(lds + PG8_SB(b, h) + boff + n * 2048 + k * 1024); } while (0)
; #define PG8_MMA(ai, bj, At, Bt) do { __builtin_amdgcn_s_setprio(1); _Pragma("unroll") for (int m = 0; m < 4; ++m) _Pragma("unroll") for (int n = 0; n < 2; ++n) _Pragma("unroll") for (int k = 0; k < 2; ++k) \
;         acc[ai][bj][m][n] = __builtin_amdgcn_mfma_f32_16x16x32_bf16(Bt[n][k], At[m][k], acc[ai][bj][m][n], 0, 0, 0); __builtin_amdgcn_s_setprio(0); } while (0)
; #define PG8_WAIT_V(n) asm volatile("s_waitcnt vmcnt(" #n ")" ::: "memory")
; #define PG8_WAIT_L(n) asm volatile("s_waitcnt lgkmcnt(" #n ")" ::: "memory")
; template <class Epi, class Sched, bool ALIGN_EPI = false, bool SP2 = false, bool PAIR_ACC = false>
; __device__ __forceinline__ void gemm_phase(PG8_LAS unsigned char* lds, const Gemm g, const Sched& S, const Epi& E) {
;     ...
;         const char* nA = has_next ? (const char*)g.A + (size_t)nxt.pm * tstep + (size_t)(nxt.pn / g.a_div) * g.a_sel : cA; const char* nB = has_next ? (const char*)g.Bt + (size_t)nxt.pn * tstep : cB;
;         for (int t = 0; t < nt; t += 2) {
;             const bool last = (t == nt - 2);
;             const char* a1 = cA + (size_t)(t + 1) * kstep;
;             const char* a2 = last ? nA : cA + (size_t)(t + 2) * kstep; const char* b2 = last ? nB : cB + (size_t)(t + 2) * kstep;
;             const char* a3 = a2 + kstep; const char* b3 = b2 + kstep;
;             if (last && has_next) S.a_ready(nxt);
;             if constexpr (SP2) {
;             PG8_LDB(B0, 0, 0); PG8_LDB(B1, 0, 1); PG8_SCHED; PG8_LDA(At, 0, 0); PG8_STAGE(PG8_SA(1, 1), a1 + hstep, voffA);
;             PG8_WAIT_V(8); PG8_WAIT_L(0); PG8_BAR; PG8_MMA(0, 0, At, B0); PG8_MMA(0, 1, At, B1); PG8_BAR; PG8_SCHED;
.LBB0_1736:
	s_ashr_i32 s53, s52, 31
	s_lshl_b64 s[10:11], s[52:53], 19
	s_add_u32 s54, s4, s10
	s_addc_u32 s55, s5, s11
	s_and_b64 s[10:11], s[8:9], exec
	s_cselect_b32 s53, s55, s63
	s_cselect_b32 s75, s54, s62
	s_ashr_i32 s51, s50, 31
	s_lshl_b64 s[10:11], s[50:51], 19
	s_add_u32 s56, s24, s10
	s_addc_u32 s57, s25, s11
	s_and_b64 s[10:11], s[8:9], exec
	s_cselect_b32 s51, s57, s61
	s_cselect_b32 s76, s56, s60
	s_add_u32 s10, s62, 0x40080
	s_addc_u32 s11, s63, 0
	s_add_u32 s77, s60, 0x100
	s_addc_u32 s78, s61, 0
	s_mov_b32 s79, -2
	s_waitcnt vmcnt(0)
	ds_read_b128 v[74:77], v196
	ds_read_b128 v[78:81], v196 offset:1024
	ds_read_b128 v[82:85], v196 offset:2048
	ds_read_b128 v[86:89], v196 offset:3072
	ds_read_b128 v[90:93], v197
	ds_read_b128 v[94:97], v197 offset:1024
	ds_read_b128 v[98:101], v197 offset:2048
	ds_read_b128 v[106:109], v197 offset:3072
	s_add_u32 s60, s10, 0xfffc0080
	s_addc_u32 s61, s11, -1
	s_cmp_eq_u32 s79, 12
	s_cselect_b32 s63, s53, s61
	s_cselect_b32 s62, s75, s60
	s_cselect_b32 s61, s51, s78
	s_cselect_b32 s60, s76, s77
	v_lshl_add_u64 v[170:171], s[10:11], 0, v[184:185]
	s_add_i32 m0, s36, 0xc000
	ds_read_b128 v[162:165], v198
	ds_read_b128 v[166:169], v198 offset:1024
	ds_read_b128 v[204:207], v198 offset:2048
	ds_read_b128 v[208:211], v198 offset:3072
	ds_read_b128 v[212:215], v198 offset:4096
	ds_read_b128 v[216:219], v198 offset:5120
	ds_read_b128 v[220:223], v198 offset:6144
	ds_read_b128 v[224:227], v198 offset:7168
	global_load_lds_dwordx4 v[170:171], off
	v_lshl_add_u64 v[170:171], s[10:11], 0, v[186:187]
	s_add_i32 m0, s36, 0xe000
	s_nop 0
	global_load_lds_dwordx4 v[170:171], off
	s_waitcnt vmcnt(8)
	s_waitcnt lgkmcnt(0)
	s_barrier
	s_setprio 1
	s_waitcnt lgkmcnt(0)
	v_mfma_f32_16x16x32_bf16 v[150:153], v[74:77], v[162:165], 0
	v_mfma_f32_16x16x32_bf16 v[146:149], v[82:85], v[162:165], 0
	v_mfma_f32_16x16x32_bf16 v[134:137], v[74:77], v[204:207], 0
	v_mfma_f32_16x16x32_bf16 v[130:133], v[82:85], v[204:207], 0
	v_mfma_f32_16x16x32_bf16 v[118:121], v[74:77], v[212:215], 0
	v_mfma_f32_16x16x32_bf16 v[110:113], v[82:85], v[212:215], 0
	v_mfma_f32_16x16x32_bf16 v[114:117], v[74:77], v[220:223], 0
	v_mfma_f32_16x16x32_bf16 v[102:105], v[82:85], v[220:223], 0
	v_mfma_f32_16x16x32_bf16 v[150:153], v[78:81], v[166:169], v[150:153]
	v_mfma_f32_16x16x32_bf16 v[146:149], v[86:89], v[166:169], v[146:149]
	v_mfma_f32_16x16x32_bf16 v[134:137], v[78:81], v[208:211], v[134:137]
	v_mfma_f32_16x16x32_bf16 v[130:133], v[86:89], v[208:211], v[130:133]
	v_mfma_f32_16x16x32_bf16 v[118:121], v[78:81], v[216:219], v[118:121]
	v_mfma_f32_16x16x32_bf16 v[110:113], v[86:89], v[216:219], v[110:113]
	v_mfma_f32_16x16x32_bf16 v[114:117], v[78:81], v[224:227], v[114:117]
	v_mfma_f32_16x16x32_bf16 v[102:105], v[86:89], v[224:227], v[102:105]
	s_setprio 0
	s_setprio 1
	v_mfma_f32_16x16x32_bf16 v[158:161], v[90:93], v[162:165], 0
	v_mfma_f32_16x16x32_bf16 v[154:157], v[98:101], v[162:165], 0
	v_mfma_f32_16x16x32_bf16 v[142:145], v[90:93], v[204:207], 0
	v_mfma_f32_16x16x32_bf16 v[138:141], v[98:101], v[204:207], 0
	v_mfma_f32_16x16x32_bf16 v[126:129], v[90:93], v[212:215], 0
	v_mfma_f32_16x16x32_bf16 v[122:125], v[98:101], v[212:215], 0
	v_mfma_f32_16x16x32_bf16 v[70:73], v[90:93], v[220:223], 0
	v_mfma_f32_16x16x32_bf16 v[66:69], v[98:101], v[220:223], 0
	v_mfma_f32_16x16x32_bf16 v[158:161], v[94:97], v[166:169], v[158:161]
	v_mfma_f32_16x16x32_bf16 v[154:157], v[106:109], v[166:169], v[154:157]
	v_mfma_f32_16x16x32_bf16 v[142:145], v[94:97], v[208:211], v[142:145]
	v_mfma_f32_16x16x32_bf16 v[138:141], v[106:109], v[208:211], v[138:141]
	v_mfma_f32_16x16x32_bf16 v[126:129], v[94:97], v[216:219], v[126:129]
	v_mfma_f32_16x16x32_bf16 v[122:125], v[106:109], v[216:219], v[122:125]
	v_mfma_f32_16x16x32_bf16 v[70:73], v[94:97], v[224:227], v[70:73]
	v_mfma_f32_16x16x32_bf16 v[66:69], v[106:109], v[224:227], v[66:69]
	s_setprio 0
	s_barrier
; #define PG8_STAGE(bufoff, gbase, voff) do { _Pragma("unroll") for (int _i = 0; _i < 2; ++_i) \
;         __builtin_amdgcn_global_load_lds((const unsigned*)((const char*)(gbase) + (voff)[_i]), (PG8_LAS unsigned*)(lds + (bufoff) + ldsw + _i * 8192), 16, 0, 0); } while (0)
; #define PG8_LDA(dst, b, h) do { _Pragma("unroll") for (int m = 0; m < 4; ++m) _Pragma("unroll") for (int k = 0; k < 2; ++k) dst[m][k] = *(const PG8_LAS bf16x8*)(lds + PG8_SA(b, h) + aoff + m * 2048 + k * 1024); } while (0)
; #define PG8_MMA(ai, bj, At, Bt) do { __builtin_amdgcn_s_setprio(1); _Pragma("unroll") for (int m = 0; m < 4; ++m) _Pragma("unroll") for (int n = 0; n < 2; ++n) _Pragma("unroll") for (int k = 0; k < 2; ++k) \
;         acc[ai][bj][m][n] = __builtin_amdgcn_mfma_f32_16x16x32_bf16(Bt[n][k], At[m][k], acc[ai][bj][m][n], 0, 0, 0); __builtin_amdgcn_s_setprio(0); } while (0)
; #define PG8_WAIT_V(n) asm volatile("s_waitcnt vmcnt(" #n ")" ::: "memory")
; #define PG8_WAIT_L(n) asm volatile("s_waitcnt lgkmcnt(" #n ")" ::: "memory")
; #define PG8_BAR __builtin_amdgcn_s_barrier()
; #define PG8_SCHED __builtin_amdgcn_sched_barrier(0)
; template <class Epi, class Sched, bool ALIGN_EPI = false, bool SP2 = false, bool PAIR_ACC = false>
; __device__ __forceinline__ void gemm_phase(PG8_LAS unsigned char* lds, const Gemm g, const Sched& S, const Epi& E) {
;     ...
;             PG8_LDA(At, 0, 1); PG8_STAGE(PG8_SB(0, 0), b2, voffB); PG8_STAGE(PG8_SB(0, 1), b2 + hstep, voffB); PG8_STAGE(PG8_SA(0, 0), a2, voffA);
;             PG8_WAIT_V(8); PG8_WAIT_L(0); PG8_BAR; PG8_MMA(1, 0, At, B0); PG8_MMA(1, 1, At, B1); PG8_BAR; PG8_SCHED;
	s_add_i32 s80, s70, s34
	v_lshl_add_u64 v[170:171], s[60:61], 0, v[176:177]
	s_mov_b32 m0, s80
	ds_read_b128 v[162:165], v198 offset:16384
	ds_read_b128 v[166:169], v198 offset:17408
	ds_read_b128 v[204:207], v198 offset:18432
	ds_read_b128 v[208:211], v198 offset:19456
	ds_read_b128 v[212:215], v198 offset:20480
	ds_read_b128 v[216:219], v198 offset:21504
	ds_read_b128 v[220:223], v198 offset:22528
	ds_read_b128 v[224:227], v198 offset:23552
	global_load_lds_dwordx4 v[170:171], off
	s_add_i32 m0, s80, 0x2000
	s_add_u32 s80, s60, 0x40000
	v_lshl_add_u64 v[192:193], s[60:61], 0, v[172:173]
	s_addc_u32 s81, s61, 0
	s_add_i32 s82, s71, s34
	global_load_lds_dwordx4 v[192:193], off
	v_lshl_add_u64 v[228:229], s[80:81], 0, v[176:177]
	s_mov_b32 m0, s82
	v_lshl_add_u64 v[230:231], s[62:63], 0, v[174:175]
	global_load_lds_dwordx4 v[228:229], off
	v_lshl_add_u64 v[228:229], s[80:81], 0, v[172:173]
	s_add_i32 m0, s82, 0x2000
	s_nop 0
	global_load_lds_dwordx4 v[228:229], off
	v_lshl_add_u64 v[228:229], s[62:63], 0, v[178:179]
	s_mov_b32 m0, s36
	s_nop 0
	global_load_lds_dwordx4 v[228:229], off
	s_mov_b32 m0, s37
	s_nop 0
	global_load_lds_dwordx4 v[230:231], off
	s_waitcnt vmcnt(8)
	s_waitcnt lgkmcnt(0)
	s_barrier
	s_setprio 1
	s_waitcnt lgkmcnt(0)
	v_mfma_f32_16x16x32_bf16 v[54:57], v[74:77], v[162:165], 0
	v_mfma_f32_16x16x32_bf16 v[50:53], v[82:85], v[162:165], 0
	v_mfma_f32_16x16x32_bf16 v[38:41], v[74:77], v[204:207], 0
	v_mfma_f32_16x16x32_bf16 v[34:37], v[82:85], v[204:207], 0
	v_mfma_f32_16x16x32_bf16 v[22:25], v[74:77], v[212:215], 0
	v_mfma_f32_16x16x32_bf16 v[14:17], v[82:85], v[212:215], 0
	v_mfma_f32_16x16x32_bf16 v[18:21], v[74:77], v[220:223], 0
	v_mfma_f32_16x16x32_bf16 v[10:13], v[82:85], v[220:223], 0
	v_mfma_f32_16x16x32_bf16 v[54:57], v[78:81], v[166:169], v[54:57]
	v_mfma_f32_16x16x32_bf16 v[50:53], v[86:89], v[166:169], v[50:53]
	v_mfma_f32_16x16x32_bf16 v[38:41], v[78:81], v[208:211], v[38:41]
	v_mfma_f32_16x16x32_bf16 v[34:37], v[86:89], v[208:211], v[34:37]
	v_mfma_f32_16x16x32_bf16 v[22:25], v[78:81], v[216:219], v[22:25]
	v_mfma_f32_16x16x32_bf16 v[14:17], v[86:89], v[216:219], v[14:17]
	v_mfma_f32_16x16x32_bf16 v[18:21], v[78:81], v[224:227], v[18:21]
	v_mfma_f32_16x16x32_bf16 v[10:13], v[86:89], v[224:227], v[10:13]
	s_setprio 0
	s_setprio 1
	v_mfma_f32_16x16x32_bf16 v[62:65], v[90:93], v[162:165], 0
	v_mfma_f32_16x16x32_bf16 v[58:61], v[98:101], v[162:165], 0
	v_mfma_f32_16x16x32_bf16 v[46:49], v[90:93], v[204:207], 0
	v_mfma_f32_16x16x32_bf16 v[42:45], v[98:101], v[204:207], 0
	v_mfma_f32_16x16x32_bf16 v[30:33], v[90:93], v[212:215], 0
	v_mfma_f32_16x16x32_bf16 v[26:29], v[98:101], v[212:215], 0
	v_mfma_f32_16x16x32_bf16 v[6:9], v[90:93], v[220:223], 0
	v_mfma_f32_16x16x32_bf16 v[2:5], v[98:101], v[220:223], 0
	v_mfma_f32_16x16x32_bf16 v[62:65], v[94:97], v[166:169], v[62:65]
	v_mfma_f32_16x16x32_bf16 v[58:61], v[106:109], v[166:169], v[58:61]
	v_mfma_f32_16x16x32_bf16 v[46:49], v[94:97], v[208:211], v[46:49]
	v_mfma_f32_16x16x32_bf16 v[42:45], v[106:109], v[208:211], v[42:45]
	v_mfma_f32_16x16x32_bf16 v[30:33], v[94:97], v[216:219], v[30:33]
	v_mfma_f32_16x16x32_bf16 v[26:29], v[106:109], v[216:219], v[26:29]
	v_mfma_f32_16x16x32_bf16 v[6:9], v[94:97], v[224:227], v[6:9]
	v_mfma_f32_16x16x32_bf16 v[2:5], v[106:109], v[224:227], v[2:5]
	s_setprio 0
	s_barrier
	s_branch .Lpeel_mid_1737

; #define PG8_STAGE(bufoff, gbase, voff) do { _Pragma("unroll") for (int _i = 0; _i < 2; ++_i) \
;         __builtin_amdgcn_global_load_lds((const unsigned*)((const char*)(gbase) + (voff)[_i]), (PG8_LAS unsigned*)(lds + (bufoff) + ldsw + _i * 8192), 16, 0, 0); } while (0)
; #define PG8_LDA(dst, b, h) do { _Pragma("unroll") for (int m = 0; m < 4; ++m) _Pragma("unroll") for (int k = 0; k < 2; ++k) dst[m][k] = *(const PG8_LAS bf16x8*)(lds + PG8_SA(b, h) + aoff + m * 2048 + k * 1024); } while (0)
; #define PG8_LDB(dst, b, h) do { _Pragma("unroll") for (int n = 0; n < 2; ++n) _Pragma("unroll") for (int k = 0; k < 2; ++k) dst[n][k] = *(const PG8_LAS bf16x8*)(lds + PG8_SB(b, h) + boff + n * 2048 + k * 1024); } while (0)
; #define PG8_MMA(ai, bj, At, Bt) do { __builtin_amdgcn_s_setprio(1); _Pragma("unroll") for (int m = 0; m < 4; ++m) _Pragma("unroll") for (int n = 0; n < 2; ++n) _Pragma("unroll") for (int k = 0; k < 2; ++k) \
;         acc[ai][bj][m][n] = __builtin_amdgcn_mfma_f32_16x16x32_bf16(Bt[n][k], At[m][k], acc[ai][bj][m][n], 0, 0, 0); __builtin_amdgcn_s_setprio(0); } while (0)
; #define PG8_WAIT_V(n) asm volatile("s_waitcnt vmcnt(" #n ")" ::: "memory")
; #define PG8_WAIT_L(n) asm volatile("s_waitcnt lgkmcnt(" #n ")" ::: "memory")
; #define PG8_BAR __builtin_amdgcn_s_barrier()
; #define PG8_SCHED __builtin_amdgcn_sched_barrier(0)
; template <class Epi, class Sched, bool ALIGN_EPI = false, bool SP2 = false, bool PAIR_ACC = false>
; __device__ __forceinline__ void gemm_phase(PG8_LAS unsigned char* lds, const Gemm g, const Sched& S, const Epi& E) {
;     ...
;             PG8_LDB(B0, 1, 0); PG8_LDB(B1, 1, 1); PG8_SCHED; PG8_LDA(At, 1, 0); PG8_STAGE(PG8_SA(0, 1), a2 + hstep, voffA);
;             PG8_WAIT_V(8); PG8_WAIT_L(0); PG8_BAR; PG8_MMA(0, 0, At, B0); PG8_MMA(0, 1, At, B1); PG8_BAR; PG8_SCHED;
.Lpeel_mid_1737:
	s_add_i32 s80, 0, 0x18000
	s_add_i32 s81, 0, 0x1c000
	v_add_u32_e32 v86, s80, v194
	v_add_u32_e32 v106, s81, v194
	ds_read_b128 v[74:77], v86
	ds_read_b128 v[78:81], v86 offset:1024
	ds_read_b128 v[82:85], v86 offset:2048
	ds_read_b128 v[86:89], v86 offset:3072
	ds_read_b128 v[90:93], v106
	ds_read_b128 v[94:97], v106 offset:1024
	ds_read_b128 v[98:101], v106 offset:2048
	ds_read_b128 v[106:109], v106 offset:3072
	s_add_u32 s62, s62, 0x40000
	s_addc_u32 s63, s63, 0
	s_mov_b32 m0, s49
	v_lshl_add_u64 v[232:233], s[62:63], 0, v[178:179]
	ds_read_b128 v[162:165], v198 offset:32768
	ds_read_b128 v[166:169], v198 offset:33792
	ds_read_b128 v[204:207], v198 offset:34816
	ds_read_b128 v[208:211], v198 offset:35840
	ds_read_b128 v[212:215], v198 offset:36864
	ds_read_b128 v[216:219], v198 offset:37888
	ds_read_b128 v[220:223], v198 offset:38912
	ds_read_b128 v[224:227], v198 offset:39936
	global_load_lds_dwordx4 v[232:233], off
	v_lshl_add_u64 v[232:233], s[62:63], 0, v[174:175]
	s_mov_b32 m0, s64
	s_nop 0
	global_load_lds_dwordx4 v[232:233], off
	s_waitcnt vmcnt(8)
	s_waitcnt lgkmcnt(0)
	s_barrier
	s_setprio 1
	s_waitcnt lgkmcnt(0)
	v_mfma_f32_16x16x32_bf16 v[150:153], v[74:77], v[162:165], v[150:153]
	v_mfma_f32_16x16x32_bf16 v[146:149], v[82:85], v[162:165], v[146:149]
	v_mfma_f32_16x16x32_bf16 v[134:137], v[74:77], v[204:207], v[134:137]
	v_mfma_f32_16x16x32_bf16 v[130:133], v[82:85], v[204:207], v[130:133]
	v_mfma_f32_16x16x32_bf16 v[118:121], v[74:77], v[212:215], v[118:121]
	v_mfma_f32_16x16x32_bf16 v[110:113], v[82:85], v[212:215], v[110:113]
	v_mfma_f32_16x16x32_bf16 v[114:117], v[74:77], v[220:223], v[114:117]
	v_mfma_f32_16x16x32_bf16 v[102:105], v[82:85], v[220:223], v[102:105]
	v_mfma_f32_16x16x32_bf16 v[150:153], v[78:81], v[166:169], v[150:153]
	v_mfma_f32_16x16x32_bf16 v[146:149], v[86:89], v[166:169], v[146:149]
	v_mfma_f32_16x16x32_bf16 v[134:137], v[78:81], v[208:211], v[134:137]
	v_mfma_f32_16x16x32_bf16 v[130:133], v[86:89], v[208:211], v[130:133]
	v_mfma_f32_16x16x32_bf16 v[118:121], v[78:81], v[216:219], v[118:121]
	v_mfma_f32_16x16x32_bf16 v[110:113], v[86:89], v[216:219], v[110:113]
	v_mfma_f32_16x16x32_bf16 v[114:117], v[78:81], v[224:227], v[114:117]
	v_mfma_f32_16x16x32_bf16 v[102:105], v[86:89], v[224:227], v[102:105]
	s_setprio 0
	s_setprio 1
	v_mfma_f32_16x16x32_bf16 v[158:161], v[90:93], v[162:165], v[158:161]
	v_mfma_f32_16x16x32_bf16 v[154:157], v[98:101], v[162:165], v[154:157]
	v_mfma_f32_16x16x32_bf16 v[142:145], v[90:93], v[204:207], v[142:145]
	v_mfma_f32_16x16x32_bf16 v[138:141], v[98:101], v[204:207], v[138:141]
	v_mfma_f32_16x16x32_bf16 v[126:129], v[90:93], v[212:215], v[126:129]
	v_mfma_f32_16x16x32_bf16 v[122:125], v[98:101], v[212:215], v[122:125]
	v_mfma_f32_16x16x32_bf16 v[70:73], v[90:93], v[220:223], v[70:73]
	v_mfma_f32_16x16x32_bf16 v[66:69], v[98:101], v[220:223], v[66:69]
	v_mfma_f32_16x16x32_bf16 v[158:161], v[94:97], v[166:169], v[158:161]
	v_mfma_f32_16x16x32_bf16 v[154:157], v[106:109], v[166:169], v[154:157]
	v_mfma_f32_16x16x32_bf16 v[142:145], v[94:97], v[208:211], v[142:145]
	v_mfma_f32_16x16x32_bf16 v[138:141], v[106:109], v[208:211], v[138:141]
	v_mfma_f32_16x16x32_bf16 v[126:129], v[94:97], v[216:219], v[126:129]
	v_mfma_f32_16x16x32_bf16 v[122:125], v[106:109], v[216:219], v[122:125]
	v_mfma_f32_16x16x32_bf16 v[70:73], v[94:97], v[224:227], v[70:73]
	v_mfma_f32_16x16x32_bf16 v[66:69], v[106:109], v[224:227], v[66:69]
	s_setprio 0
	s_barrier
; #define PG8_STAGE(bufoff, gbase, voff) do { _Pragma("unroll") for (int _i = 0; _i < 2; ++_i) \
;         __builtin_amdgcn_global_load_lds((const unsigned*)((const char*)(gbase) + (voff)[_i]), (PG8_LAS unsigned*)(lds + (bufoff) + ldsw + _i * 8192), 16, 0, 0); } while (0)
; #define PG8_LDA(dst, b, h) do { _Pragma("unroll") for (int m = 0; m < 4; ++m) _Pragma("unroll") for (int k = 0; k < 2; ++k) dst[m][k] = *(const PG8_LAS bf16x8*)(lds + PG8_SA(b, h) + aoff + m * 2048 + k * 1024); } while (0)
; #define PG8_MMA(ai, bj, At, Bt) do { __builtin_amdgcn_s_setprio(1); _Pragma("unroll") for (int m = 0; m < 4; ++m) _Pragma("unroll") for (int n = 0; n < 2; ++n) _Pragma("unroll") for (int k = 0; k < 2; ++k) \
;         acc[ai][bj][m][n] = __builtin_amdgcn_mfma_f32_16x16x32_bf16(Bt[n][k], At[m][k], acc[ai][bj][m][n], 0, 0, 0); __builtin_amdgcn_s_setprio(0); } while (0)
; #define PG8_WAIT_V(n) asm volatile("s_waitcnt vmcnt(" #n ")" ::: "memory")
; #define PG8_WAIT_L(n) asm volatile("s_waitcnt lgkmcnt(" #n ")" ::: "memory")
; #define PG8_BAR __builtin_amdgcn_s_barrier()
; #define PG8_SCHED __builtin_amdgcn_sched_barrier(0)
; template <class Epi, class Sched, bool ALIGN_EPI = false, bool SP2 = false, bool PAIR_ACC = false>
; __device__ __forceinline__ void gemm_phase(PG8_LAS unsigned char* lds, const Gemm g, const Sched& S, const Epi& E) {
;     ...
;             PG8_LDA(At, 1, 1); PG8_STAGE(PG8_SB(1, 0), b3, voffB); PG8_STAGE(PG8_SB(1, 1), b3 + hstep, voffB); PG8_STAGE(PG8_SA(1, 0), a3, voffA);
;             PG8_WAIT_V(8); PG8_WAIT_L(0); PG8_BAR; PG8_MMA(1, 0, At, B0); PG8_MMA(1, 1, At, B1); PG8_BAR; PG8_SCHED;
;     ...
;         if constexpr (ALIGN_EPI) { if (wr == 0) PG8_BAR; }
	s_add_i32 s62, s80, s34
	v_lshl_add_u64 v[170:171], v[170:171], 0, s[30:31]
	s_mov_b32 m0, s62
	ds_read_b128 v[162:165], v198 offset:49152
	ds_read_b128 v[166:169], v198 offset:50176
	ds_read_b128 v[204:207], v198 offset:51200
	ds_read_b128 v[208:211], v198 offset:52224
	ds_read_b128 v[212:215], v198 offset:53248
	ds_read_b128 v[216:219], v198 offset:54272
	ds_read_b128 v[220:223], v198 offset:55296
	ds_read_b128 v[224:227], v198 offset:56320
	global_load_lds_dwordx4 v[170:171], off
	s_add_i32 m0, s62, 0x2000
	s_add_u32 s60, s60, 0x40080
	v_lshl_add_u64 v[170:171], v[192:193], 0, s[30:31]
	s_addc_u32 s61, s61, 0
	s_add_i32 s62, s81, s34
	global_load_lds_dwordx4 v[170:171], off
	v_lshl_add_u64 v[170:171], s[60:61], 0, v[176:177]
	s_mov_b32 m0, s62
	s_nop 0
	global_load_lds_dwordx4 v[170:171], off
	v_lshl_add_u64 v[170:171], s[60:61], 0, v[172:173]
	s_add_i32 m0, s62, 0x2000
	s_nop 0
	global_load_lds_dwordx4 v[170:171], off
	v_lshl_add_u64 v[170:171], v[228:229], 0, s[30:31]
	s_mov_b32 m0, s68
	s_nop 0
	global_load_lds_dwordx4 v[170:171], off
	v_lshl_add_u64 v[170:171], v[230:231], 0, s[30:31]
	s_mov_b32 m0, s69
	s_nop 0
	global_load_lds_dwordx4 v[170:171], off
	s_waitcnt vmcnt(8)
	s_waitcnt lgkmcnt(0)
	s_barrier
	s_setprio 1
	s_waitcnt lgkmcnt(0)
	v_mfma_f32_16x16x32_bf16 v[54:57], v[74:77], v[162:165], v[54:57]
	v_mfma_f32_16x16x32_bf16 v[50:53], v[82:85], v[162:165], v[50:53]
	v_mfma_f32_16x16x32_bf16 v[38:41], v[74:77], v[204:207], v[38:41]
	v_mfma_f32_16x16x32_bf16 v[34:37], v[82:85], v[204:207], v[34:37]
	v_mfma_f32_16x16x32_bf16 v[22:25], v[74:77], v[212:215], v[22:25]
	v_mfma_f32_16x16x32_bf16 v[14:17], v[82:85], v[212:215], v[14:17]
	v_mfma_f32_16x16x32_bf16 v[18:21], v[74:77], v[220:223], v[18:21]
	v_mfma_f32_16x16x32_bf16 v[10:13], v[82:85], v[220:223], v[10:13]
	v_mfma_f32_16x16x32_bf16 v[54:57], v[78:81], v[166:169], v[54:57]
	v_mfma_f32_16x16x32_bf16 v[50:53], v[86:89], v[166:169], v[50:53]
	v_mfma_f32_16x16x32_bf16 v[38:41], v[78:81], v[208:211], v[38:41]
	v_mfma_f32_16x16x32_bf16 v[34:37], v[86:89], v[208:211], v[34:37]
	v_mfma_f32_16x16x32_bf16 v[22:25], v[78:81], v[216:219], v[22:25]
	v_mfma_f32_16x16x32_bf16 v[14:17], v[86:89], v[216:219], v[14:17]
	v_mfma_f32_16x16x32_bf16 v[18:21], v[78:81], v[224:227], v[18:21]
	v_mfma_f32_16x16x32_bf16 v[10:13], v[86:89], v[224:227], v[10:13]
	s_setprio 0
	s_setprio 1
	v_mfma_f32_16x16x32_bf16 v[62:65], v[90:93], v[162:165], v[62:65]
	v_mfma_f32_16x16x32_bf16 v[58:61], v[98:101], v[162:165], v[58:61]
	v_mfma_f32_16x16x32_bf16 v[46:49], v[90:93], v[204:207], v[46:49]
	v_mfma_f32_16x16x32_bf16 v[42:45], v[98:101], v[204:207], v[42:45]
	v_mfma_f32_16x16x32_bf16 v[30:33], v[90:93], v[212:215], v[30:33]
	v_mfma_f32_16x16x32_bf16 v[26:29], v[98:101], v[212:215], v[26:29]
	v_mfma_f32_16x16x32_bf16 v[6:9], v[90:93], v[220:223], v[6:9]
	v_mfma_f32_16x16x32_bf16 v[2:5], v[98:101], v[220:223], v[2:5]
	v_mfma_f32_16x16x32_bf16 v[62:65], v[94:97], v[166:169], v[62:65]
	v_mfma_f32_16x16x32_bf16 v[58:61], v[106:109], v[166:169], v[58:61]
	v_mfma_f32_16x16x32_bf16 v[46:49], v[94:97], v[208:211], v[46:49]
	v_mfma_f32_16x16x32_bf16 v[42:45], v[106:109], v[208:211], v[42:45]
	v_mfma_f32_16x16x32_bf16 v[30:33], v[94:97], v[216:219], v[30:33]
	v_mfma_f32_16x16x32_bf16 v[26:29], v[106:109], v[216:219], v[26:29]
	v_mfma_f32_16x16x32_bf16 v[6:9], v[94:97], v[224:227], v[6:9]
	v_mfma_f32_16x16x32_bf16 v[2:5], v[106:109], v[224:227], v[2:5]
	s_setprio 0
	s_barrier
	s_add_i32 s79, s79, 2
	s_add_u32 s10, s10, 0x100
	s_addc_u32 s11, s11, 0
	s_add_u32 s77, s77, 0x100
	s_addc_u32 s78, s78, 0
	s_cmp_gt_u32 s79, 13
	s_cbranch_scc0 .LBB0_1737
	s_and_b64 vcc, exec, s[38:39]
	s_cbranch_vccz .LBB0_1740
	s_barrier
